# Down/Out residual epilogues: row sum-of-squares cross-lane reduction via v_permlane16_swap / v_permlane32_swap instead of two ds_bpermute LDS round trips with lgkmcnt waits (bit-identical sums)
# speedup vs baseline: 1.0024x; 1.0024x over previous
; __device__ __forceinline__ float lane_xor(float v, int lane, int o) { return __builtin_bit_cast(float, __builtin_amdgcn_ds_bpermute((lane ^ o) << 2, __builtin_bit_cast(int, v))); }
; __device__ __forceinline__ unsigned cvt_pk_bf16(float lo, float hi) { unsigned r; asm volatile("v_cvt_pk_bf16_f32 %0, %1, %2" : "=v"(r) : "v"(lo), "v"(hi)); return r; }
;     __device__ __forceinline__ void operator()(const f32x4 (&acc)[2][2][4][2], const Unit& u, int wr, int wc, int fr_in, int fq_in) const {
;     ...
;             for (int m = 0; m < 4; ++m) {
;                 const int row = row0 + ai * HALF + m * 16;
;                 bf16_t* xp = XN + (size_t)row * DM + col0;
;                 float sq = 0.f;
; #pragma unroll
;                 for (int bj = 0; bj < 2; ++bj) {
;                     const f32x4 a = hv[m][bj][0] + acc[ai][bj][m][0] * alpha, b = hv[m][bj][1] + acc[ai][bj][m][1] * alpha;
;                     *(f32x4*)(hp[m] + bj * HALF) = a; *(f32x4*)(hp[m] + bj * HALF + 4) = b;
;                     sq += (a[0] * a[0] + a[1] * a[1]) + (a[2] * a[2] + a[3] * a[3]) + (b[0] * b[0] + b[1] * b[1]) + (b[2] * b[2] + b[3] * b[3]);
;                     const f32x4 xa = a * gv[bj][0], xb = b * gv[bj][1];
;                     u32x4 w; w.x = cvt_pk_bf16(xa[0], xa[1]); w.y = cvt_pk_bf16(xa[2], xa[3]); w.z = cvt_pk_bf16(xb[0], xb[1]); w.w = cvt_pk_bf16(xb[2], xb[3]);
;                     *(u32x4*)(xp + bj * HALF) = w;
;                 }
;                 sq += lane_xor(sq, lane, 16); sq += lane_xor(sq, lane, 32);
;                 if (fq == 0) atomicAdd(SSout + row, sq);
;             }
.LBB0_307:
	s_or_b64 exec, exec, s[4:5]
	v_lshlrev_b64 v[236:237], 2, v[232:233]
	v_lshl_add_u64 v[146:147], v[148:149], 0, v[236:237]
	flat_load_dwordx4 v[174:177], v[146:147]
	flat_load_dwordx4 v[166:169], v[146:147] offset:16
	flat_load_dwordx4 v[150:153], v[146:147] offset:512
	s_nop 0
	flat_load_dwordx4 v[146:149], v[146:147] offset:528
	v_lshlrev_b32_e32 v0, 2, v239
	v_bfrev_b32_e32 v214, 0.5
	s_movk_i32 s4, 0x80
	s_waitcnt vmcnt(0) lgkmcnt(0)
	v_pk_fma_f32 v[144:145], v[144:145], 0.5, v[208:209] op_sel_hi:[1,0,1]
	v_pk_fma_f32 v[142:143], v[142:143], 0.5, v[206:207] op_sel_hi:[1,0,1]
	v_lshl_add_u64 v[212:213], v[250:251], 0, v[236:237]
	v_bitop3_b32 v251, v0, 64, v214 bitop3:0x6c
	v_bitop3_b32 v250, v0, s4, v214 bitop3:0x6c
	v_pk_fma_f32 v[138:139], v[138:139], 0.5, v[202:203] op_sel_hi:[1,0,1]
	v_mul_f32_e32 v0, v143, v143
	v_mul_f32_e32 v202, v145, v145
	v_fmac_f32_e32 v0, v142, v142
	v_fmac_f32_e32 v202, v144, v144
	v_add_f32_e32 v0, v0, v202
	v_mul_f32_e32 v202, v139, v139
	v_cmp_eq_u32_e32 vcc, 0, v235
	v_ashrrev_i32_e32 v235, 31, v234
	v_pk_fma_f32 v[140:141], v[140:141], 0.5, v[204:205] op_sel_hi:[1,0,1]
	v_fmac_f32_e32 v202, v138, v138
	v_lshlrev_b64 v[214:215], 11, v[234:235]
	v_add_f32_e32 v0, v202, v0
	v_mul_f32_e32 v202, v141, v141
	v_lshl_add_u64 v[214:215], s[58:59], 0, v[214:215]
	v_fmac_f32_e32 v202, v140, v140
	v_lshl_add_u64 v[214:215], v[232:233], 1, v[214:215]
	flat_store_dwordx4 v[212:213], v[142:145]
	flat_store_dwordx4 v[212:213], v[138:141] offset:16
	v_add_f32_e32 v0, v202, v0
	v_pk_mul_f32 v[144:145], v[80:81], v[144:145]
	v_pk_mul_f32 v[142:143], v[78:79], v[142:143]
	v_pk_mul_f32 v[202:203], v[76:77], v[140:141]
	v_pk_mul_f32 v[140:141], v[74:75], v[138:139]
	v_cvt_pk_bf16_f32 v138, v142, v143
	v_cvt_pk_bf16_f32 v139, v144, v145
	v_pk_fma_f32 v[136:137], v[136:137], 0.5, v[192:193] op_sel_hi:[1,0,1]
	v_pk_fma_f32 v[134:135], v[134:135], 0.5, v[190:191] op_sel_hi:[1,0,1]
	v_cvt_pk_bf16_f32 v140, v140, v141
	v_cvt_pk_bf16_f32 v141, v202, v203
	flat_store_dwordx4 v[214:215], v[138:141]
	v_pk_fma_f32 v[130:131], v[130:131], 0.5, v[186:187] op_sel_hi:[1,0,1]
	v_pk_fma_f32 v[132:133], v[132:133], 0.5, v[188:189] op_sel_hi:[1,0,1]
	v_mul_f32_e32 v138, v135, v135
	v_mul_f32_e32 v139, v137, v137
	v_fmac_f32_e32 v138, v134, v134
	v_fmac_f32_e32 v139, v136, v136
	v_add_f32_e32 v138, v138, v139
	v_mul_f32_e32 v139, v131, v131
	v_fmac_f32_e32 v139, v130, v130
	v_add_f32_e32 v138, v139, v138
	v_mul_f32_e32 v139, v133, v133
	v_fmac_f32_e32 v139, v132, v132
	v_add_f32_e32 v138, v139, v138
	v_add_f32_e32 v0, v0, v138
	flat_store_dwordx4 v[212:213], v[134:137] offset:512
	flat_store_dwordx4 v[212:213], v[130:133] offset:528
	v_pk_mul_f32 v[140:141], v[66:67], v[130:131]
	v_pk_mul_f32 v[134:135], v[70:71], v[134:135]
	v_lshl_add_u64 v[186:187], v[234:235], 2, s[10:11]
	s_nop 1
	v_mov_b32_e32 v142, v0
	s_nop 1
	v_permlane16_swap_b32_e32 v0, v142
	v_add_f32_e32 v0, v0, v142
	v_mov_b32_e32 v130, v0
	s_nop 1
	v_permlane32_swap_b32_e32 v0, v130
	v_add_f32_e32 v0, v0, v130
	v_pk_mul_f32 v[136:137], v[72:73], v[136:137]
	v_pk_mul_f32 v[138:139], v[68:69], v[132:133]
	v_cvt_pk_bf16_f32 v132, v134, v135
	v_cvt_pk_bf16_f32 v133, v136, v137
	v_cvt_pk_bf16_f32 v134, v140, v141
	s_nop 0
	v_cvt_pk_bf16_f32 v135, v138, v139
	flat_store_dwordx4 v[214:215], v[132:135] offset:256
	s_and_saveexec_b64 s[4:5], vcc
	s_cbranch_execz .LBB0_309
	flat_atomic_add_f32 v[186:187], v0
.LBB0_309:
	s_or_b64 exec, exec, s[4:5]
	v_pk_fma_f32 v[128:129], v[128:129], 0.5, v[200:201] op_sel_hi:[1,0,1]
	v_pk_fma_f32 v[126:127], v[126:127], 0.5, v[198:199] op_sel_hi:[1,0,1]
	v_mul_f32_e32 v134, v129, v129
	v_mul_f32_e32 v0, v127, v127
	v_pk_fma_f32 v[122:123], v[122:123], 0.5, v[194:195] op_sel_hi:[1,0,1]
	v_fmac_f32_e32 v0, v126, v126
	v_fmac_f32_e32 v134, v128, v128
	v_add_f32_e32 v0, v0, v134
	v_mul_f32_e32 v134, v123, v123
	v_ashrrev_i32_e32 v245, 31, v244
	v_pk_fma_f32 v[124:125], v[124:125], 0.5, v[196:197] op_sel_hi:[1,0,1]
	v_fmac_f32_e32 v134, v122, v122
	v_lshlrev_b64 v[132:133], 11, v[244:245]
	v_add_f32_e32 v0, v134, v0
	v_mul_f32_e32 v134, v125, v125
	s_waitcnt lgkmcnt(0)
	v_lshl_add_u64 v[130:131], v[232:233], 2, v[248:249]
	v_lshl_add_u64 v[132:133], s[58:59], 0, v[132:133]
	v_fmac_f32_e32 v134, v124, v124
	v_lshl_add_u64 v[132:133], v[232:233], 1, v[132:133]
	flat_store_dwordx4 v[130:131], v[126:129]
	flat_store_dwordx4 v[130:131], v[122:125] offset:16
	v_add_f32_e32 v0, v134, v0
	v_pk_mul_f32 v[128:129], v[80:81], v[128:129]
	v_pk_mul_f32 v[126:127], v[78:79], v[126:127]
	v_pk_mul_f32 v[134:135], v[76:77], v[124:125]
	v_pk_mul_f32 v[124:125], v[74:75], v[122:123]
	v_cvt_pk_bf16_f32 v122, v126, v127
	v_cvt_pk_bf16_f32 v123, v128, v129
	v_pk_fma_f32 v[120:121], v[120:121], 0.5, v[172:173] op_sel_hi:[1,0,1]
	v_pk_fma_f32 v[118:119], v[118:119], 0.5, v[170:171] op_sel_hi:[1,0,1]
	v_cvt_pk_bf16_f32 v124, v124, v125
	v_cvt_pk_bf16_f32 v125, v134, v135
	flat_store_dwordx4 v[132:133], v[122:125]
	v_pk_fma_f32 v[114:115], v[114:115], 0.5, v[162:163] op_sel_hi:[1,0,1]
	v_pk_fma_f32 v[116:117], v[116:117], 0.5, v[164:165] op_sel_hi:[1,0,1]
	v_mul_f32_e32 v122, v119, v119
	v_mul_f32_e32 v123, v121, v121
	v_fmac_f32_e32 v122, v118, v118
	v_fmac_f32_e32 v123, v120, v120
	v_add_f32_e32 v122, v122, v123
	v_mul_f32_e32 v123, v115, v115
	v_fmac_f32_e32 v123, v114, v114
	v_add_f32_e32 v122, v123, v122
	v_mul_f32_e32 v123, v117, v117
	v_fmac_f32_e32 v123, v116, v116
	v_add_f32_e32 v122, v123, v122
	v_add_f32_e32 v0, v0, v122
	flat_store_dwordx4 v[130:131], v[118:121] offset:512
	flat_store_dwordx4 v[130:131], v[114:117] offset:528
	v_pk_mul_f32 v[124:125], v[66:67], v[114:115]
	v_pk_mul_f32 v[118:119], v[70:71], v[118:119]
	v_pk_mul_f32 v[120:121], v[72:73], v[120:121]
	s_nop 1
	v_mov_b32_e32 v126, v0
	s_nop 1
	v_permlane16_swap_b32_e32 v0, v126
	v_add_f32_e32 v0, v0, v126
	v_mov_b32_e32 v114, v0
	s_nop 1
	v_permlane32_swap_b32_e32 v0, v114
	v_add_f32_e32 v0, v0, v114
	v_pk_mul_f32 v[122:123], v[68:69], v[116:117]
	v_cvt_pk_bf16_f32 v116, v118, v119
	v_cvt_pk_bf16_f32 v117, v120, v121
	v_cvt_pk_bf16_f32 v118, v124, v125
	s_nop 0
	v_cvt_pk_bf16_f32 v119, v122, v123
	flat_store_dwordx4 v[132:133], v[116:119] offset:256
	s_and_saveexec_b64 s[4:5], vcc
	s_cbranch_execz .LBB0_311
	flat_atomic_add_f32 v[186:187], v0 offset:64
; __device__ __forceinline__ float lane_xor(float v, int lane, int o) { return __builtin_bit_cast(float, __builtin_amdgcn_ds_bpermute((lane ^ o) << 2, __builtin_bit_cast(int, v))); }
; __device__ __forceinline__ unsigned cvt_pk_bf16(float lo, float hi) { unsigned r; asm volatile("v_cvt_pk_bf16_f32 %0, %1, %2" : "=v"(r) : "v"(lo), "v"(hi)); return r; }
;     __device__ __forceinline__ void operator()(const f32x4 (&acc)[2][2][4][2], const Unit& u, int wr, int wc, int fr_in, int fq_in) const {
;     ...
;             for (int m = 0; m < 4; ++m) {
;                 const int row = row0 + ai * HALF + m * 16;
;                 bf16_t* xp = XN + (size_t)row * DM + col0;
;                 float sq = 0.f;
; #pragma unroll
;                 for (int bj = 0; bj < 2; ++bj) {
;                     const f32x4 a = hv[m][bj][0] + acc[ai][bj][m][0] * alpha, b = hv[m][bj][1] + acc[ai][bj][m][1] * alpha;
;                     *(f32x4*)(hp[m] + bj * HALF) = a; *(f32x4*)(hp[m] + bj * HALF + 4) = b;
;                     sq += (a[0] * a[0] + a[1] * a[1]) + (a[2] * a[2] + a[3] * a[3]) + (b[0] * b[0] + b[1] * b[1]) + (b[2] * b[2] + b[3] * b[3]);
;                     const f32x4 xa = a * gv[bj][0], xb = b * gv[bj][1];
;                     u32x4 w; w.x = cvt_pk_bf16(xa[0], xa[1]); w.y = cvt_pk_bf16(xa[2], xa[3]); w.z = cvt_pk_bf16(xb[0], xb[1]); w.w = cvt_pk_bf16(xb[2], xb[3]);
;                     *(u32x4*)(xp + bj * HALF) = w;
;                 }
;                 sq += lane_xor(sq, lane, 16); sq += lane_xor(sq, lane, 32);
;                 if (fq == 0) atomicAdd(SSout + row, sq);
;             }
.LBB0_311:
	s_or_b64 exec, exec, s[4:5]
	v_pk_fma_f32 v[112:113], v[112:113], 0.5, v[184:185] op_sel_hi:[1,0,1]
	v_pk_fma_f32 v[110:111], v[110:111], 0.5, v[182:183] op_sel_hi:[1,0,1]
	v_mul_f32_e32 v118, v113, v113
	v_mul_f32_e32 v0, v111, v111
	v_pk_fma_f32 v[106:107], v[106:107], 0.5, v[178:179] op_sel_hi:[1,0,1]
	v_fmac_f32_e32 v0, v110, v110
	v_fmac_f32_e32 v118, v112, v112
	v_add_f32_e32 v0, v0, v118
	v_mul_f32_e32 v118, v107, v107
	v_ashrrev_i32_e32 v241, 31, v240
	v_pk_fma_f32 v[108:109], v[108:109], 0.5, v[180:181] op_sel_hi:[1,0,1]
	v_fmac_f32_e32 v118, v106, v106
	v_lshlrev_b64 v[116:117], 11, v[240:241]
	v_add_f32_e32 v0, v118, v0
	v_mul_f32_e32 v118, v109, v109
	s_waitcnt lgkmcnt(0)
	v_lshl_add_u64 v[114:115], v[232:233], 2, v[246:247]
	v_lshl_add_u64 v[116:117], s[58:59], 0, v[116:117]
	v_fmac_f32_e32 v118, v108, v108
	v_lshl_add_u64 v[116:117], v[232:233], 1, v[116:117]
	flat_store_dwordx4 v[114:115], v[110:113]
	flat_store_dwordx4 v[114:115], v[106:109] offset:16
	v_add_f32_e32 v0, v118, v0
	v_pk_mul_f32 v[112:113], v[80:81], v[112:113]
	v_pk_mul_f32 v[110:111], v[78:79], v[110:111]
	v_pk_mul_f32 v[118:119], v[76:77], v[108:109]
	v_pk_mul_f32 v[108:109], v[74:75], v[106:107]
	v_cvt_pk_bf16_f32 v106, v110, v111
	v_cvt_pk_bf16_f32 v107, v112, v113
	v_pk_fma_f32 v[104:105], v[104:105], 0.5, v[160:161] op_sel_hi:[1,0,1]
	v_pk_fma_f32 v[102:103], v[102:103], 0.5, v[158:159] op_sel_hi:[1,0,1]
	v_cvt_pk_bf16_f32 v108, v108, v109
	v_cvt_pk_bf16_f32 v109, v118, v119
	flat_store_dwordx4 v[116:117], v[106:109]
	v_pk_fma_f32 v[98:99], v[98:99], 0.5, v[154:155] op_sel_hi:[1,0,1]
	v_pk_fma_f32 v[100:101], v[100:101], 0.5, v[156:157] op_sel_hi:[1,0,1]
	v_mul_f32_e32 v106, v103, v103
	v_mul_f32_e32 v107, v105, v105
	v_fmac_f32_e32 v106, v102, v102
	v_fmac_f32_e32 v107, v104, v104
	v_add_f32_e32 v106, v106, v107
	v_mul_f32_e32 v107, v99, v99
	v_fmac_f32_e32 v107, v98, v98
	v_add_f32_e32 v106, v107, v106
	v_mul_f32_e32 v107, v101, v101
	v_fmac_f32_e32 v107, v100, v100
	v_add_f32_e32 v106, v107, v106
	v_add_f32_e32 v0, v0, v106
	flat_store_dwordx4 v[114:115], v[102:105] offset:512
	flat_store_dwordx4 v[114:115], v[98:101] offset:528
	v_pk_mul_f32 v[108:109], v[66:67], v[98:99]
	v_pk_mul_f32 v[102:103], v[70:71], v[102:103]
	v_pk_mul_f32 v[104:105], v[72:73], v[104:105]
	s_nop 1
	v_mov_b32_e32 v110, v0
	s_nop 1
	v_permlane16_swap_b32_e32 v0, v110
	v_add_f32_e32 v0, v0, v110
	v_mov_b32_e32 v98, v0
	s_nop 1
	v_permlane32_swap_b32_e32 v0, v98
	v_add_f32_e32 v0, v0, v98
	v_pk_mul_f32 v[106:107], v[68:69], v[100:101]
	v_cvt_pk_bf16_f32 v100, v102, v103
	v_cvt_pk_bf16_f32 v101, v104, v105
	v_cvt_pk_bf16_f32 v102, v108, v109
	s_nop 0
	v_cvt_pk_bf16_f32 v103, v106, v107
	flat_store_dwordx4 v[116:117], v[100:103] offset:256
	s_and_saveexec_b64 s[4:5], vcc
	s_cbranch_execz .LBB0_313
	flat_atomic_add_f32 v[186:187], v0 offset:128
.LBB0_313:
	s_or_b64 exec, exec, s[4:5]
	v_pk_fma_f32 v[96:97], v[96:97], 0.5, v[176:177] op_sel_hi:[1,0,1]
	v_pk_fma_f32 v[94:95], v[94:95], 0.5, v[174:175] op_sel_hi:[1,0,1]
	v_mul_f32_e32 v102, v97, v97
	v_mul_f32_e32 v0, v95, v95
	v_pk_fma_f32 v[90:91], v[90:91], 0.5, v[166:167] op_sel_hi:[1,0,1]
	v_fmac_f32_e32 v0, v94, v94
	v_fmac_f32_e32 v102, v96, v96
	v_add_f32_e32 v0, v0, v102
	v_mul_f32_e32 v102, v91, v91
	v_ashrrev_i32_e32 v239, 31, v238
	v_pk_fma_f32 v[92:93], v[92:93], 0.5, v[168:169] op_sel_hi:[1,0,1]
	v_fmac_f32_e32 v102, v90, v90
	v_lshlrev_b64 v[100:101], 11, v[238:239]
	v_add_f32_e32 v0, v102, v0
	v_mul_f32_e32 v102, v93, v93
	s_waitcnt lgkmcnt(0)
	v_lshl_add_u64 v[98:99], v[232:233], 2, v[242:243]
	v_lshl_add_u64 v[100:101], s[58:59], 0, v[100:101]
	v_fmac_f32_e32 v102, v92, v92
	v_lshl_add_u64 v[100:101], v[232:233], 1, v[100:101]
	flat_store_dwordx4 v[98:99], v[94:97]
	flat_store_dwordx4 v[98:99], v[90:93] offset:16
	v_add_f32_e32 v0, v102, v0
	v_pk_mul_f32 v[96:97], v[80:81], v[96:97]
	v_pk_mul_f32 v[94:95], v[78:79], v[94:95]
	v_pk_mul_f32 v[102:103], v[76:77], v[92:93]
	v_pk_mul_f32 v[92:93], v[74:75], v[90:91]
	v_cvt_pk_bf16_f32 v90, v94, v95
	v_cvt_pk_bf16_f32 v91, v96, v97
	v_pk_fma_f32 v[88:89], v[88:89], 0.5, v[152:153] op_sel_hi:[1,0,1]
	v_pk_fma_f32 v[86:87], v[86:87], 0.5, v[150:151] op_sel_hi:[1,0,1]
	v_cvt_pk_bf16_f32 v92, v92, v93
	v_cvt_pk_bf16_f32 v93, v102, v103
	flat_store_dwordx4 v[100:101], v[90:93]
	v_pk_fma_f32 v[82:83], v[82:83], 0.5, v[146:147] op_sel_hi:[1,0,1]
	v_pk_fma_f32 v[84:85], v[84:85], 0.5, v[148:149] op_sel_hi:[1,0,1]
	v_mul_f32_e32 v90, v87, v87
	v_mul_f32_e32 v91, v89, v89
	v_fmac_f32_e32 v90, v86, v86
	v_fmac_f32_e32 v91, v88, v88
	v_add_f32_e32 v90, v90, v91
	v_mul_f32_e32 v91, v83, v83
	v_fmac_f32_e32 v91, v82, v82
	v_add_f32_e32 v90, v91, v90
	v_mul_f32_e32 v91, v85, v85
	v_fmac_f32_e32 v91, v84, v84
	v_add_f32_e32 v90, v91, v90
	v_add_f32_e32 v0, v0, v90
	flat_store_dwordx4 v[98:99], v[86:89] offset:512
	flat_store_dwordx4 v[98:99], v[82:85] offset:528
	v_pk_mul_f32 v[92:93], v[66:67], v[82:83]
	v_pk_mul_f32 v[86:87], v[70:71], v[86:87]
	v_pk_mul_f32 v[88:89], v[72:73], v[88:89]
	s_nop 1
	v_mov_b32_e32 v94, v0
	s_nop 1
	v_permlane16_swap_b32_e32 v0, v94
	v_add_f32_e32 v0, v0, v94
	v_mov_b32_e32 v82, v0
	s_nop 1
	v_permlane32_swap_b32_e32 v0, v82
	v_add_f32_e32 v0, v0, v82
	v_pk_mul_f32 v[90:91], v[68:69], v[84:85]
	v_cvt_pk_bf16_f32 v84, v86, v87
	v_cvt_pk_bf16_f32 v85, v88, v89
	v_cvt_pk_bf16_f32 v86, v92, v93
	s_nop 0
	v_cvt_pk_bf16_f32 v87, v90, v91
	flat_store_dwordx4 v[100:101], v[84:87] offset:256
	s_and_saveexec_b64 s[4:5], vcc
	s_cbranch_execz .LBB0_315
	flat_atomic_add_f32 v[186:187], v0 offset:192

; __device__ __forceinline__ float lane_xor(float v, int lane, int o) { return __builtin_bit_cast(float, __builtin_amdgcn_ds_bpermute((lane ^ o) << 2, __builtin_bit_cast(int, v))); }
; __device__ __forceinline__ unsigned cvt_pk_bf16(float lo, float hi) { unsigned r; asm volatile("v_cvt_pk_bf16_f32 %0, %1, %2" : "=v"(r) : "v"(lo), "v"(hi)); return r; }
;     __device__ __forceinline__ void operator()(const f32x4 (&acc)[2][2][4][2], const Unit& u, int wr, int wc, int fr_in, int fq_in) const {
;     ...
;             for (int m = 0; m < 4; ++m) { const int rw = row0 + ai * HALF + m * 16; hp[m] = hrow(LEAD, OUT, rw) + col0;
;                 const float* sp = hp[m];
;                 if (XP) { const int b = rw / LP, sl = rw - b * LP; if (sl >= 128) sp = (b < 2 ? XP + ((size_t)b * SEQ + (sl - 128)) * DM : XS + ((size_t)(b - 2) * SEQ + (sl - 128)) * DM) + col0; }
; #pragma unroll
;                 for (int bj = 0; bj < 2; ++bj) { hv[m][bj][0] = *(const f32x4*)(sp + bj * HALF); hv[m][bj][1] = *(const f32x4*)(sp + bj * HALF + 4); } }
; #pragma unroll
;             for (int m = 0; m < 4; ++m) {
;                 const int row = row0 + ai * HALF + m * 16;
;                 bf16_t* xp = XN + (size_t)row * DM + col0;
;                 float sq = 0.f;
; #pragma unroll
;                 for (int bj = 0; bj < 2; ++bj) {
;                     const f32x4 a = hv[m][bj][0] + acc[ai][bj][m][0] * alpha, b = hv[m][bj][1] + acc[ai][bj][m][1] * alpha;
;                     *(f32x4*)(hp[m] + bj * HALF) = a; *(f32x4*)(hp[m] + bj * HALF + 4) = b;
;                     sq += (a[0] * a[0] + a[1] * a[1]) + (a[2] * a[2] + a[3] * a[3]) + (b[0] * b[0] + b[1] * b[1]) + (b[2] * b[2] + b[3] * b[3]);
;                     const f32x4 xa = a * gv[bj][0], xb = b * gv[bj][1];
;                     u32x4 w; w.x = cvt_pk_bf16(xa[0], xa[1]); w.y = cvt_pk_bf16(xa[2], xa[3]); w.z = cvt_pk_bf16(xb[0], xb[1]); w.w = cvt_pk_bf16(xb[2], xb[3]);
;                     *(u32x4*)(xp + bj * HALF) = w;
;                 }
;                 sq += lane_xor(sq, lane, 16); sq += lane_xor(sq, lane, 32);
;                 if (fq == 0) atomicAdd(SSout + row, sq);
;             }
.LBB0_355:
	s_or_b64 exec, exec, s[36:37]
	v_lshl_add_u64 v[160:161], v[82:83], 0, v[236:237]
	v_lshl_add_u64 v[82:83], v[86:87], 0, v[236:237]
	flat_load_dwordx4 v[106:109], v[82:83]
	flat_load_dwordx4 v[98:101], v[82:83] offset:16
	flat_load_dwordx4 v[86:89], v[82:83] offset:512
	s_nop 0
	flat_load_dwordx4 v[82:85], v[82:83] offset:528
	s_waitcnt vmcnt(0) lgkmcnt(0)
	v_pk_fma_f32 v[64:65], v[64:65], 0.5, v[144:145] op_sel_hi:[1,0,1]
	v_pk_fma_f32 v[62:63], v[62:63], 0.5, v[142:143] op_sel_hi:[1,0,1]
	v_pk_fma_f32 v[58:59], v[58:59], 0.5, v[138:139] op_sel_hi:[1,0,1]
	v_mul_f32_e32 v0, v63, v63
	v_mul_f32_e32 v138, v65, v65
	v_fmac_f32_e32 v0, v62, v62
	v_fmac_f32_e32 v138, v64, v64
	v_add_f32_e32 v0, v0, v138
	v_mul_f32_e32 v138, v59, v59
	v_ashrrev_i32_e32 v159, 31, v158
	v_pk_fma_f32 v[60:61], v[60:61], 0.5, v[140:141] op_sel_hi:[1,0,1]
	v_fmac_f32_e32 v138, v58, v58
	v_lshlrev_b64 v[158:159], 11, v[158:159]
	v_add_f32_e32 v0, v138, v0
	v_mul_f32_e32 v138, v61, v61
	v_lshl_add_u64 v[158:159], s[58:59], 0, v[158:159]
	v_fmac_f32_e32 v138, v60, v60
	v_lshl_add_u64 v[158:159], v[232:233], 1, v[158:159]
	flat_store_dwordx4 v[160:161], v[62:65]
	flat_store_dwordx4 v[160:161], v[58:61] offset:16
	v_add_f32_e32 v0, v138, v0
	v_pk_mul_f32 v[64:65], v[80:81], v[64:65]
	v_pk_mul_f32 v[62:63], v[78:79], v[62:63]
	v_pk_mul_f32 v[138:139], v[76:77], v[60:61]
	v_pk_mul_f32 v[60:61], v[74:75], v[58:59]
	v_cvt_pk_bf16_f32 v58, v62, v63
	v_cvt_pk_bf16_f32 v59, v64, v65
	v_pk_fma_f32 v[56:57], v[56:57], 0.5, v[136:137] op_sel_hi:[1,0,1]
	v_pk_fma_f32 v[54:55], v[54:55], 0.5, v[134:135] op_sel_hi:[1,0,1]
	v_cvt_pk_bf16_f32 v60, v60, v61
	v_cvt_pk_bf16_f32 v61, v138, v139
	flat_store_dwordx4 v[158:159], v[58:61]
	v_pk_fma_f32 v[50:51], v[50:51], 0.5, v[130:131] op_sel_hi:[1,0,1]
	v_pk_fma_f32 v[52:53], v[52:53], 0.5, v[132:133] op_sel_hi:[1,0,1]
	v_mul_f32_e32 v58, v55, v55
	v_mul_f32_e32 v59, v57, v57
	v_fmac_f32_e32 v58, v54, v54
	v_fmac_f32_e32 v59, v56, v56
	v_add_f32_e32 v58, v58, v59
	v_mul_f32_e32 v59, v51, v51
	v_fmac_f32_e32 v59, v50, v50
	v_add_f32_e32 v58, v59, v58
	v_mul_f32_e32 v59, v53, v53
	v_fmac_f32_e32 v59, v52, v52
	v_add_f32_e32 v58, v59, v58
	flat_store_dwordx4 v[160:161], v[54:57] offset:512
	flat_store_dwordx4 v[160:161], v[50:53] offset:528
	v_add_f32_e32 v0, v0, v58
	v_pk_mul_f32 v[54:55], v[70:71], v[54:55]
	v_pk_mul_f32 v[58:59], v[68:69], v[52:53]
	v_pk_mul_f32 v[52:53], v[66:67], v[50:51]
	v_cvt_pk_bf16_f32 v50, v54, v55
	v_pk_mul_f32 v[56:57], v[72:73], v[56:57]
	s_nop 0
	v_cvt_pk_bf16_f32 v51, v56, v57
	v_cvt_pk_bf16_f32 v52, v52, v53
	v_cvt_pk_bf16_f32 v53, v58, v59
	flat_store_dwordx4 v[158:159], v[50:53] offset:256
	s_nop 1
	v_mov_b32_e32 v50, v0
	s_nop 1
	v_permlane16_swap_b32_e32 v0, v50
	v_add_f32_e32 v0, v0, v50
	v_mov_b32_e32 v50, v0
	s_nop 1
	v_permlane32_swap_b32_e32 v0, v50
	v_add_f32_e32 v0, v0, v50
	s_and_saveexec_b64 s[4:5], vcc
	s_cbranch_execz .LBB0_357
	flat_atomic_add_f32 v[186:187], v0 offset:512
.LBB0_357:
	s_or_b64 exec, exec, s[4:5]
	v_pk_fma_f32 v[48:49], v[48:49], 0.5, v[128:129] op_sel_hi:[1,0,1]
	v_pk_fma_f32 v[46:47], v[46:47], 0.5, v[126:127] op_sel_hi:[1,0,1]
	v_mul_f32_e32 v54, v49, v49
	v_mul_f32_e32 v0, v47, v47
	v_pk_fma_f32 v[42:43], v[42:43], 0.5, v[122:123] op_sel_hi:[1,0,1]
	v_fmac_f32_e32 v0, v46, v46
	v_fmac_f32_e32 v54, v48, v48
	v_add_f32_e32 v0, v0, v54
	v_mul_f32_e32 v54, v43, v43
	v_ashrrev_i32_e32 v153, 31, v152
	v_pk_fma_f32 v[44:45], v[44:45], 0.5, v[124:125] op_sel_hi:[1,0,1]
	v_fmac_f32_e32 v54, v42, v42
	v_lshlrev_b64 v[52:53], 11, v[152:153]
	v_add_f32_e32 v0, v54, v0
	v_mul_f32_e32 v54, v45, v45
	s_waitcnt lgkmcnt(0)
	v_lshl_add_u64 v[50:51], v[232:233], 2, v[156:157]
	v_lshl_add_u64 v[52:53], s[58:59], 0, v[52:53]
	v_fmac_f32_e32 v54, v44, v44
	v_lshl_add_u64 v[52:53], v[232:233], 1, v[52:53]
	flat_store_dwordx4 v[50:51], v[46:49]
	flat_store_dwordx4 v[50:51], v[42:45] offset:16
	v_add_f32_e32 v0, v54, v0
	v_pk_mul_f32 v[48:49], v[80:81], v[48:49]
	v_pk_mul_f32 v[46:47], v[78:79], v[46:47]
	v_pk_mul_f32 v[54:55], v[76:77], v[44:45]
	v_pk_mul_f32 v[44:45], v[74:75], v[42:43]
	v_cvt_pk_bf16_f32 v42, v46, v47
	v_cvt_pk_bf16_f32 v43, v48, v49
	v_pk_fma_f32 v[40:41], v[40:41], 0.5, v[112:113] op_sel_hi:[1,0,1]
	v_pk_fma_f32 v[38:39], v[38:39], 0.5, v[110:111] op_sel_hi:[1,0,1]
	v_cvt_pk_bf16_f32 v44, v44, v45
	v_cvt_pk_bf16_f32 v45, v54, v55
	flat_store_dwordx4 v[52:53], v[42:45]
	v_pk_fma_f32 v[34:35], v[34:35], 0.5, v[102:103] op_sel_hi:[1,0,1]
	v_pk_fma_f32 v[36:37], v[36:37], 0.5, v[104:105] op_sel_hi:[1,0,1]
	v_mul_f32_e32 v42, v39, v39
	v_mul_f32_e32 v43, v41, v41
	v_fmac_f32_e32 v42, v38, v38
	v_fmac_f32_e32 v43, v40, v40
	v_add_f32_e32 v42, v42, v43
	v_mul_f32_e32 v43, v35, v35
	v_fmac_f32_e32 v43, v34, v34
	v_add_f32_e32 v42, v43, v42
	v_mul_f32_e32 v43, v37, v37
	v_fmac_f32_e32 v43, v36, v36
	v_add_f32_e32 v42, v43, v42
	v_add_f32_e32 v0, v0, v42
	flat_store_dwordx4 v[50:51], v[38:41] offset:512
	flat_store_dwordx4 v[50:51], v[34:37] offset:528
	v_pk_mul_f32 v[44:45], v[66:67], v[34:35]
	v_pk_mul_f32 v[38:39], v[70:71], v[38:39]
	v_pk_mul_f32 v[40:41], v[72:73], v[40:41]
	s_nop 1
	v_mov_b32_e32 v46, v0
	s_nop 1
	v_permlane16_swap_b32_e32 v0, v46
	v_add_f32_e32 v0, v0, v46
	v_mov_b32_e32 v34, v0
	s_nop 1
	v_permlane32_swap_b32_e32 v0, v34
	v_add_f32_e32 v0, v0, v34
	v_pk_mul_f32 v[42:43], v[68:69], v[36:37]
	v_cvt_pk_bf16_f32 v36, v38, v39
	v_cvt_pk_bf16_f32 v37, v40, v41
	v_cvt_pk_bf16_f32 v38, v44, v45
	s_nop 0
	v_cvt_pk_bf16_f32 v39, v42, v43
	flat_store_dwordx4 v[52:53], v[36:39] offset:256
	s_and_saveexec_b64 s[4:5], vcc
	s_cbranch_execz .LBB0_359
	flat_atomic_add_f32 v[186:187], v0 offset:576
; __device__ __forceinline__ float lane_xor(float v, int lane, int o) { return __builtin_bit_cast(float, __builtin_amdgcn_ds_bpermute((lane ^ o) << 2, __builtin_bit_cast(int, v))); }
; __device__ __forceinline__ unsigned cvt_pk_bf16(float lo, float hi) { unsigned r; asm volatile("v_cvt_pk_bf16_f32 %0, %1, %2" : "=v"(r) : "v"(lo), "v"(hi)); return r; }
;     __device__ __forceinline__ void operator()(const f32x4 (&acc)[2][2][4][2], const Unit& u, int wr, int wc, int fr_in, int fq_in) const {
;     ...
;             for (int m = 0; m < 4; ++m) {
;                 const int row = row0 + ai * HALF + m * 16;
;                 bf16_t* xp = XN + (size_t)row * DM + col0;
;                 float sq = 0.f;
; #pragma unroll
;                 for (int bj = 0; bj < 2; ++bj) {
;                     const f32x4 a = hv[m][bj][0] + acc[ai][bj][m][0] * alpha, b = hv[m][bj][1] + acc[ai][bj][m][1] * alpha;
;                     *(f32x4*)(hp[m] + bj * HALF) = a; *(f32x4*)(hp[m] + bj * HALF + 4) = b;
;                     sq += (a[0] * a[0] + a[1] * a[1]) + (a[2] * a[2] + a[3] * a[3]) + (b[0] * b[0] + b[1] * b[1]) + (b[2] * b[2] + b[3] * b[3]);
;                     const f32x4 xa = a * gv[bj][0], xb = b * gv[bj][1];
;                     u32x4 w; w.x = cvt_pk_bf16(xa[0], xa[1]); w.y = cvt_pk_bf16(xa[2], xa[3]); w.z = cvt_pk_bf16(xb[0], xb[1]); w.w = cvt_pk_bf16(xb[2], xb[3]);
;                     *(u32x4*)(xp + bj * HALF) = w;
;                 }
;                 sq += lane_xor(sq, lane, 16); sq += lane_xor(sq, lane, 32);
;                 if (fq == 0) atomicAdd(SSout + row, sq);
;             }
.LBB0_359:
	s_or_b64 exec, exec, s[4:5]
	v_pk_fma_f32 v[32:33], v[32:33], 0.5, v[120:121] op_sel_hi:[1,0,1]
	v_pk_fma_f32 v[30:31], v[30:31], 0.5, v[118:119] op_sel_hi:[1,0,1]
	v_mul_f32_e32 v38, v33, v33
	v_mul_f32_e32 v0, v31, v31
	v_pk_fma_f32 v[26:27], v[26:27], 0.5, v[114:115] op_sel_hi:[1,0,1]
	v_fmac_f32_e32 v0, v30, v30
	v_fmac_f32_e32 v38, v32, v32
	v_add_f32_e32 v0, v0, v38
	v_mul_f32_e32 v38, v27, v27
	v_ashrrev_i32_e32 v149, 31, v148
	v_pk_fma_f32 v[28:29], v[28:29], 0.5, v[116:117] op_sel_hi:[1,0,1]
	v_fmac_f32_e32 v38, v26, v26
	v_lshlrev_b64 v[36:37], 11, v[148:149]
	v_add_f32_e32 v0, v38, v0
	v_mul_f32_e32 v38, v29, v29
	s_waitcnt lgkmcnt(0)
	v_lshl_add_u64 v[34:35], v[232:233], 2, v[154:155]
	v_lshl_add_u64 v[36:37], s[58:59], 0, v[36:37]
	v_fmac_f32_e32 v38, v28, v28
	v_lshl_add_u64 v[36:37], v[232:233], 1, v[36:37]
	flat_store_dwordx4 v[34:35], v[30:33]
	flat_store_dwordx4 v[34:35], v[26:29] offset:16
	v_add_f32_e32 v0, v38, v0
	v_pk_mul_f32 v[32:33], v[80:81], v[32:33]
	v_pk_mul_f32 v[30:31], v[78:79], v[30:31]
	v_pk_mul_f32 v[38:39], v[76:77], v[28:29]
	v_pk_mul_f32 v[28:29], v[74:75], v[26:27]
	v_cvt_pk_bf16_f32 v26, v30, v31
	v_cvt_pk_bf16_f32 v27, v32, v33
	v_pk_fma_f32 v[24:25], v[24:25], 0.5, v[96:97] op_sel_hi:[1,0,1]
	v_pk_fma_f32 v[22:23], v[22:23], 0.5, v[94:95] op_sel_hi:[1,0,1]
	v_cvt_pk_bf16_f32 v28, v28, v29
	v_cvt_pk_bf16_f32 v29, v38, v39
	flat_store_dwordx4 v[36:37], v[26:29]
	v_pk_fma_f32 v[18:19], v[18:19], 0.5, v[90:91] op_sel_hi:[1,0,1]
	v_pk_fma_f32 v[20:21], v[20:21], 0.5, v[92:93] op_sel_hi:[1,0,1]
	v_mul_f32_e32 v26, v23, v23
	v_mul_f32_e32 v27, v25, v25
	v_fmac_f32_e32 v26, v22, v22
	v_fmac_f32_e32 v27, v24, v24
	v_add_f32_e32 v26, v26, v27
	v_mul_f32_e32 v27, v19, v19
	v_fmac_f32_e32 v27, v18, v18
	v_add_f32_e32 v26, v27, v26
	v_mul_f32_e32 v27, v21, v21
	v_fmac_f32_e32 v27, v20, v20
	v_add_f32_e32 v26, v27, v26
	v_add_f32_e32 v0, v0, v26
	flat_store_dwordx4 v[34:35], v[22:25] offset:512
	flat_store_dwordx4 v[34:35], v[18:21] offset:528
	v_pk_mul_f32 v[28:29], v[66:67], v[18:19]
	v_pk_mul_f32 v[22:23], v[70:71], v[22:23]
	v_pk_mul_f32 v[24:25], v[72:73], v[24:25]
	s_nop 1
	v_mov_b32_e32 v30, v0
	s_nop 1
	v_permlane16_swap_b32_e32 v0, v30
	v_add_f32_e32 v0, v0, v30
	v_mov_b32_e32 v18, v0
	s_nop 1
	v_permlane32_swap_b32_e32 v0, v18
	v_add_f32_e32 v0, v0, v18
	v_pk_mul_f32 v[26:27], v[68:69], v[20:21]
	v_cvt_pk_bf16_f32 v20, v22, v23
	v_cvt_pk_bf16_f32 v21, v24, v25
	v_cvt_pk_bf16_f32 v22, v28, v29
	s_nop 0
	v_cvt_pk_bf16_f32 v23, v26, v27
	flat_store_dwordx4 v[36:37], v[20:23] offset:256
	s_and_saveexec_b64 s[4:5], vcc
	s_cbranch_execz .LBB0_361
	flat_atomic_add_f32 v[186:187], v0 offset:640
.LBB0_361:
	s_or_b64 exec, exec, s[4:5]
	v_pk_fma_f32 v[16:17], v[16:17], 0.5, v[108:109] op_sel_hi:[1,0,1]
	v_pk_fma_f32 v[14:15], v[14:15], 0.5, v[106:107] op_sel_hi:[1,0,1]
	v_mul_f32_e32 v22, v17, v17
	v_mul_f32_e32 v0, v15, v15
	v_pk_fma_f32 v[10:11], v[10:11], 0.5, v[98:99] op_sel_hi:[1,0,1]
	v_fmac_f32_e32 v0, v14, v14
	v_fmac_f32_e32 v22, v16, v16
	v_add_f32_e32 v0, v0, v22
	v_mul_f32_e32 v22, v11, v11
	v_ashrrev_i32_e32 v147, 31, v146
	v_pk_fma_f32 v[12:13], v[12:13], 0.5, v[100:101] op_sel_hi:[1,0,1]
	v_fmac_f32_e32 v22, v10, v10
	v_lshlrev_b64 v[20:21], 11, v[146:147]
	v_add_f32_e32 v0, v22, v0
	v_mul_f32_e32 v22, v13, v13
	s_waitcnt lgkmcnt(0)
	v_lshl_add_u64 v[18:19], v[232:233], 2, v[150:151]
	v_lshl_add_u64 v[20:21], s[58:59], 0, v[20:21]
	v_fmac_f32_e32 v22, v12, v12
	v_lshl_add_u64 v[20:21], v[232:233], 1, v[20:21]
	flat_store_dwordx4 v[18:19], v[14:17]
	flat_store_dwordx4 v[18:19], v[10:13] offset:16
	v_add_f32_e32 v0, v22, v0
	v_pk_mul_f32 v[16:17], v[80:81], v[16:17]
	v_pk_mul_f32 v[14:15], v[78:79], v[14:15]
	v_pk_mul_f32 v[22:23], v[76:77], v[12:13]
	v_pk_mul_f32 v[12:13], v[74:75], v[10:11]
	v_cvt_pk_bf16_f32 v10, v14, v15
	v_cvt_pk_bf16_f32 v11, v16, v17
	v_pk_fma_f32 v[8:9], v[8:9], 0.5, v[88:89] op_sel_hi:[1,0,1]
	v_pk_fma_f32 v[6:7], v[6:7], 0.5, v[86:87] op_sel_hi:[1,0,1]
	v_cvt_pk_bf16_f32 v12, v12, v13
	v_cvt_pk_bf16_f32 v13, v22, v23
	flat_store_dwordx4 v[20:21], v[10:13]
	v_pk_fma_f32 v[2:3], v[2:3], 0.5, v[82:83] op_sel_hi:[1,0,1]
	v_pk_fma_f32 v[4:5], v[4:5], 0.5, v[84:85] op_sel_hi:[1,0,1]
	v_mul_f32_e32 v10, v7, v7
	v_mul_f32_e32 v11, v9, v9
	v_fmac_f32_e32 v10, v6, v6
	v_fmac_f32_e32 v11, v8, v8
	v_add_f32_e32 v10, v10, v11
	v_mul_f32_e32 v11, v3, v3
	v_fmac_f32_e32 v11, v2, v2
	v_add_f32_e32 v10, v11, v10
	v_mul_f32_e32 v11, v5, v5
	v_fmac_f32_e32 v11, v4, v4
	v_add_f32_e32 v10, v11, v10
	v_add_f32_e32 v0, v0, v10
	flat_store_dwordx4 v[18:19], v[6:9] offset:512
	flat_store_dwordx4 v[18:19], v[2:5] offset:528
	v_pk_mul_f32 v[12:13], v[66:67], v[2:3]
	v_pk_mul_f32 v[6:7], v[70:71], v[6:7]
	v_pk_mul_f32 v[8:9], v[72:73], v[8:9]
	s_nop 1
	v_mov_b32_e32 v14, v0
	s_nop 1
	v_permlane16_swap_b32_e32 v0, v14
	v_add_f32_e32 v0, v0, v14
	v_mov_b32_e32 v2, v0
	s_nop 1
	v_permlane32_swap_b32_e32 v0, v2
	v_add_f32_e32 v0, v0, v2
	v_pk_mul_f32 v[10:11], v[68:69], v[4:5]
	v_cvt_pk_bf16_f32 v4, v6, v7
	v_cvt_pk_bf16_f32 v5, v8, v9
	v_cvt_pk_bf16_f32 v6, v12, v13
	s_nop 0
	v_cvt_pk_bf16_f32 v7, v10, v11
	flat_store_dwordx4 v[20:21], v[4:7] offset:256
	s_and_saveexec_b64 s[4:5], vcc
	s_cbranch_execz .LBB0_363
	flat_atomic_add_f32 v[186:187], v0 offset:704

;     __device__ __forceinline__ void operator()(const f32x4 (&acc)[2][2][4][2], const Unit& u, int wr, int wc, int fr_in, int fq_in) const {
;         int t_ = threadIdx.x; asm volatile("" : "+v"(t_)); const int fr = t_ & 15, fq = (t_ >> 4) & 3, lane = t_ & 63;
;         const int row0 = u.pm * BM + wr * 64 + fr, col0 = u.pn * BM + wc * 32 + 8 * fq;
;         f32x4 gv[2][2];
; #pragma unroll
;         for (int bj = 0; bj < 2; ++bj) { gv[bj][0] = *(const f32x4*)(gain + col0 + bj * HALF); gv[bj][1] = *(const f32x4*)(gain + col0 + bj * HALF + 4); }
; #pragma unroll
;         for (int ai = 0; ai < 2; ++ai) {
;             float* hp[4]; f32x4 hv[4][2][2];
; #pragma unroll
;             for (int m = 0; m < 4; ++m) { const int rw = row0 + ai * HALF + m * 16; hp[m] = hrow(LEAD, OUT, rw) + col0;
;                 const float* sp = hp[m];
;                 if (XP) { const int b = rw / LP, sl = rw - b * LP; if (sl >= 128) sp = (b < 2 ? XP + ((size_t)b * SEQ + (sl - 128)) * DM : XS + ((size_t)(b - 2) * SEQ + (sl - 128)) * DM) + col0; }
; #pragma unroll
;                 for (int bj = 0; bj < 2; ++bj) { hv[m][bj][0] = *(const f32x4*)(sp + bj * HALF); hv[m][bj][1] = *(const f32x4*)(sp + bj * HALF + 4); } }
.LBB0_1082:
	v_mov_b32_e32 v239, v252
	s_lshl_b32 s5, s26, 8
	v_bfe_u32 v235, v239, 4, 2
	v_lshl_or_b32 v0, v235, 3, s5
	v_or_b32_e32 v232, s64, v0
	v_ashrrev_i32_e32 v233, 31, v232
	v_lshl_add_u64 v[70:71], v[232:233], 2, s[8:9]
	global_load_dwordx4 v[74:77], v[70:71], off offset:16
	global_load_dwordx4 v[78:81], v[70:71], off
	global_load_dwordx4 v[66:69], v[70:71], off offset:528
	s_nop 0
	global_load_dwordx4 v[70:73], v[70:71], off offset:512
	s_lshl_b32 s4, s4, 8
	s_add_i32 s4, s4, s63
	v_and_or_b32 v234, v239, 15, s4
	v_mul_hi_i32 v0, v234, s33
	v_lshrrev_b32_e32 v146, 31, v0
	v_ashrrev_i32_e32 v0, 12, v0
	v_add_u32_e32 v148, v0, v146
	v_mad_i32_i24 v0, v148, s51, v234
	v_cmp_lt_i32_e32 vcc, s3, v0
	s_and_saveexec_b64 s[4:5], vcc
	s_xor_b64 s[4:5], exec, s[4:5]
	v_readlane_b32 s86, v254, 51
	v_ashrrev_i32_e32 v149, 31, v148
	v_add_u32_e32 v0, 0xffffff80, v0
	v_lshlrev_b64 v[146:147], 25, v[148:149]
	v_lshl_add_u64 v[150:151], s[56:57], 0, v[146:147]
	v_mov_b64_e32 v[146:147], v[0:1]
	s_andn2_saveexec_b64 s[4:5], s[4:5]
	v_lshl_add_u32 v146, v148, 7, v0
	v_ashrrev_i32_e32 v147, 31, v146
	v_mov_b64_e32 v[150:151], s[18:19]
	s_or_b64 exec, exec, s[4:5]
	v_lshlrev_b64 v[146:147], 12, v[146:147]
	v_lshl_add_u64 v[146:147], v[150:151], 0, v[146:147]
	v_lshl_add_u64 v[248:249], v[232:233], 2, v[146:147]
	flat_load_dwordx4 v[206:209], v[248:249]
	flat_load_dwordx4 v[202:205], v[248:249] offset:16
	flat_load_dwordx4 v[198:201], v[248:249] offset:512
	flat_load_dwordx4 v[194:197], v[248:249] offset:528
	v_or_b32_e32 v246, 16, v234
	v_mul_hi_i32 v0, v246, s33
	v_lshrrev_b32_e32 v146, 31, v0
	v_ashrrev_i32_e32 v0, 12, v0
	v_add_u32_e32 v146, v0, v146
	v_mad_i32_i24 v0, v146, s51, v246
	v_cmp_lt_i32_e32 vcc, s3, v0
	s_and_saveexec_b64 s[4:5], vcc
	s_xor_b64 s[4:5], exec, s[4:5]
	v_ashrrev_i32_e32 v147, 31, v146
	v_add_u32_e32 v0, 0xffffff80, v0
	v_lshlrev_b64 v[146:147], 25, v[146:147]
	v_lshl_add_u64 v[150:151], s[56:57], 0, v[146:147]
	v_mov_b64_e32 v[148:149], v[0:1]
	s_andn2_saveexec_b64 s[4:5], s[4:5]
	v_lshl_add_u32 v148, v146, 7, v0
	v_ashrrev_i32_e32 v149, 31, v148
	v_mov_b64_e32 v[150:151], s[18:19]
	s_or_b64 exec, exec, s[4:5]
	v_lshlrev_b64 v[146:147], 12, v[148:149]
	v_lshl_add_u64 v[146:147], v[150:151], 0, v[146:147]
	v_lshl_add_u64 v[244:245], v[232:233], 2, v[146:147]
	flat_load_dwordx4 v[190:193], v[244:245]
	flat_load_dwordx4 v[186:189], v[244:245] offset:16
	flat_load_dwordx4 v[182:185], v[244:245] offset:512
	flat_load_dwordx4 v[178:181], v[244:245] offset:528
	v_or_b32_e32 v242, 32, v234
	v_mul_hi_i32 v0, v242, s33
	v_lshrrev_b32_e32 v146, 31, v0
	v_ashrrev_i32_e32 v0, 12, v0
	v_add_u32_e32 v146, v0, v146
	v_mad_i32_i24 v0, v146, s51, v242
	v_cmp_lt_i32_e32 vcc, s3, v0
	s_and_saveexec_b64 s[4:5], vcc
	s_xor_b64 s[4:5], exec, s[4:5]
	v_ashrrev_i32_e32 v147, 31, v146
	v_add_u32_e32 v0, 0xffffff80, v0
	v_lshlrev_b64 v[146:147], 25, v[146:147]
	v_lshl_add_u64 v[150:151], s[56:57], 0, v[146:147]
	v_mov_b64_e32 v[148:149], v[0:1]
	s_andn2_saveexec_b64 s[4:5], s[4:5]
	v_lshl_add_u32 v148, v146, 7, v0
	v_ashrrev_i32_e32 v149, 31, v148
	v_mov_b64_e32 v[150:151], s[18:19]
	s_or_b64 exec, exec, s[4:5]
	v_lshlrev_b64 v[146:147], 12, v[148:149]
	v_lshl_add_u64 v[146:147], v[150:151], 0, v[146:147]
	v_lshl_add_u64 v[240:241], v[232:233], 2, v[146:147]
	flat_load_dwordx4 v[174:177], v[240:241]
	flat_load_dwordx4 v[170:173], v[240:241] offset:16
	flat_load_dwordx4 v[166:169], v[240:241] offset:512
	flat_load_dwordx4 v[162:165], v[240:241] offset:528
	v_or_b32_e32 v238, 48, v234
	v_mul_hi_i32 v0, v238, s33
	v_lshrrev_b32_e32 v146, 31, v0
	v_ashrrev_i32_e32 v0, 12, v0
	v_add_u32_e32 v150, v0, v146
	v_mad_i32_i24 v0, v150, s51, v238
	v_cmp_lt_i32_e32 vcc, s3, v0
	s_and_saveexec_b64 s[4:5], vcc
	s_xor_b64 s[4:5], exec, s[4:5]
	v_ashrrev_i32_e32 v151, 31, v150
	v_add_u32_e32 v0, 0xffffff80, v0
	v_lshlrev_b64 v[146:147], 25, v[150:151]
	v_lshl_add_u64 v[148:149], s[56:57], 0, v[146:147]
	v_mov_b64_e32 v[146:147], v[0:1]
	s_andn2_saveexec_b64 s[4:5], s[4:5]
	v_lshl_add_u32 v146, v150, 7, v0
	v_ashrrev_i32_e32 v147, 31, v146
	v_mov_b64_e32 v[148:149], s[18:19]
	s_or_b64 exec, exec, s[4:5]
	v_lshlrev_b64 v[146:147], 12, v[146:147]
	v_lshl_add_u64 v[146:147], v[148:149], 0, v[146:147]
	v_lshl_add_u64 v[236:237], v[232:233], 2, v[146:147]
	flat_load_dwordx4 v[158:161], v[236:237]
	flat_load_dwordx4 v[154:157], v[236:237] offset:16
	flat_load_dwordx4 v[150:153], v[236:237] offset:512
	flat_load_dwordx4 v[146:149], v[236:237] offset:528
	v_lshlrev_b32_e32 v0, 2, v239
	v_bfrev_b32_e32 v212, 0.5
	s_movk_i32 s4, 0x80
	s_waitcnt vmcnt(0) lgkmcnt(0)
; __device__ __forceinline__ float lane_xor(float v, int lane, int o) { return __builtin_bit_cast(float, __builtin_amdgcn_ds_bpermute((lane ^ o) << 2, __builtin_bit_cast(int, v))); }
; __device__ __forceinline__ unsigned cvt_pk_bf16(float lo, float hi) { unsigned r; asm volatile("v_cvt_pk_bf16_f32 %0, %1, %2" : "=v"(r) : "v"(lo), "v"(hi)); return r; }
;     __device__ __forceinline__ void operator()(const f32x4 (&acc)[2][2][4][2], const Unit& u, int wr, int wc, int fr_in, int fq_in) const {
;     ...
;             for (int m = 0; m < 4; ++m) {
;                 const int row = row0 + ai * HALF + m * 16;
;                 bf16_t* xp = XN + (size_t)row * DM + col0;
;                 float sq = 0.f;
; #pragma unroll
;                 for (int bj = 0; bj < 2; ++bj) {
;                     const f32x4 a = hv[m][bj][0] + acc[ai][bj][m][0] * alpha, b = hv[m][bj][1] + acc[ai][bj][m][1] * alpha;
;                     *(f32x4*)(hp[m] + bj * HALF) = a; *(f32x4*)(hp[m] + bj * HALF + 4) = b;
;                     sq += (a[0] * a[0] + a[1] * a[1]) + (a[2] * a[2] + a[3] * a[3]) + (b[0] * b[0] + b[1] * b[1]) + (b[2] * b[2] + b[3] * b[3]);
;                     const f32x4 xa = a * gv[bj][0], xb = b * gv[bj][1];
;                     u32x4 w; w.x = cvt_pk_bf16(xa[0], xa[1]); w.y = cvt_pk_bf16(xa[2], xa[3]); w.z = cvt_pk_bf16(xb[0], xb[1]); w.w = cvt_pk_bf16(xb[2], xb[3]);
;                     *(u32x4*)(xp + bj * HALF) = w;
;                 }
;                 sq += lane_xor(sq, lane, 16); sq += lane_xor(sq, lane, 32);
;                 if (fq == 0) atomicAdd(SSout + row, sq);
;             }
	v_pk_add_f32 v[144:145], v[208:209], v[144:145]
	v_pk_add_f32 v[142:143], v[206:207], v[142:143]
	v_bitop3_b32 v251, v0, 64, v212 bitop3:0x6c
	v_bitop3_b32 v250, v0, s4, v212 bitop3:0x6c
	v_pk_add_f32 v[138:139], v[202:203], v[138:139]
	v_mul_f32_e32 v0, v143, v143
	v_mul_f32_e32 v202, v145, v145
	v_fmac_f32_e32 v0, v142, v142
	v_fmac_f32_e32 v202, v144, v144
	v_add_f32_e32 v0, v0, v202
	v_mul_f32_e32 v202, v139, v139
	v_cmp_eq_u32_e32 vcc, 0, v235
	v_ashrrev_i32_e32 v235, 31, v234
	v_pk_add_f32 v[140:141], v[204:205], v[140:141]
	v_fmac_f32_e32 v202, v138, v138
	v_lshlrev_b64 v[212:213], 11, v[234:235]
	v_add_f32_e32 v0, v202, v0
	v_mul_f32_e32 v202, v141, v141
	v_lshl_add_u64 v[212:213], s[58:59], 0, v[212:213]
	v_fmac_f32_e32 v202, v140, v140
	v_lshl_add_u64 v[212:213], v[232:233], 1, v[212:213]
	flat_store_dwordx4 v[248:249], v[142:145]
	flat_store_dwordx4 v[248:249], v[138:141] offset:16
	v_add_f32_e32 v0, v202, v0
	v_pk_mul_f32 v[144:145], v[80:81], v[144:145]
	v_pk_mul_f32 v[142:143], v[78:79], v[142:143]
	v_pk_mul_f32 v[202:203], v[76:77], v[140:141]
	v_pk_mul_f32 v[140:141], v[74:75], v[138:139]
	v_cvt_pk_bf16_f32 v138, v142, v143
	v_cvt_pk_bf16_f32 v139, v144, v145
	v_pk_add_f32 v[136:137], v[200:201], v[136:137]
	v_pk_add_f32 v[134:135], v[198:199], v[134:135]
	v_cvt_pk_bf16_f32 v140, v140, v141
	v_cvt_pk_bf16_f32 v141, v202, v203
	flat_store_dwordx4 v[212:213], v[138:141]
	v_pk_add_f32 v[130:131], v[194:195], v[130:131]
	v_pk_add_f32 v[132:133], v[196:197], v[132:133]
	v_mul_f32_e32 v138, v135, v135
	v_mul_f32_e32 v139, v137, v137
	v_fmac_f32_e32 v138, v134, v134
	v_fmac_f32_e32 v139, v136, v136
	v_add_f32_e32 v138, v138, v139
	v_mul_f32_e32 v139, v131, v131
	v_fmac_f32_e32 v139, v130, v130
	v_add_f32_e32 v138, v139, v138
	v_mul_f32_e32 v139, v133, v133
	v_fmac_f32_e32 v139, v132, v132
	v_add_f32_e32 v138, v139, v138
	v_add_f32_e32 v0, v0, v138
	flat_store_dwordx4 v[248:249], v[134:137] offset:512
	flat_store_dwordx4 v[248:249], v[130:133] offset:528
	v_pk_mul_f32 v[140:141], v[66:67], v[130:131]
	v_pk_mul_f32 v[134:135], v[70:71], v[134:135]
	v_lshl_add_u64 v[194:195], v[234:235], 2, s[12:13]
	s_nop 1
	v_mov_b32_e32 v142, v0
	s_nop 1
	v_permlane16_swap_b32_e32 v0, v142
	v_add_f32_e32 v0, v0, v142
	v_mov_b32_e32 v130, v0
	s_nop 1
	v_permlane32_swap_b32_e32 v0, v130
	v_add_f32_e32 v0, v0, v130
	v_pk_mul_f32 v[136:137], v[72:73], v[136:137]
	v_pk_mul_f32 v[138:139], v[68:69], v[132:133]
	v_cvt_pk_bf16_f32 v132, v134, v135
	v_cvt_pk_bf16_f32 v133, v136, v137
	v_cvt_pk_bf16_f32 v134, v140, v141
	s_nop 0
	v_cvt_pk_bf16_f32 v135, v138, v139
	flat_store_dwordx4 v[212:213], v[132:135] offset:256
	s_and_saveexec_b64 s[4:5], vcc
	s_cbranch_execz .LBB0_1100
	flat_atomic_add_f32 v[194:195], v0
.LBB0_1100:
	s_or_b64 exec, exec, s[4:5]
	v_pk_add_f32 v[128:129], v[192:193], v[128:129]
	v_pk_add_f32 v[126:127], v[190:191], v[126:127]
	v_mul_f32_e32 v132, v129, v129
	v_mul_f32_e32 v0, v127, v127
	v_pk_add_f32 v[122:123], v[186:187], v[122:123]
	v_fmac_f32_e32 v0, v126, v126
	v_fmac_f32_e32 v132, v128, v128
	v_add_f32_e32 v0, v0, v132
	v_mul_f32_e32 v132, v123, v123
	v_ashrrev_i32_e32 v247, 31, v246
	v_pk_add_f32 v[124:125], v[188:189], v[124:125]
	v_fmac_f32_e32 v132, v122, v122
	s_waitcnt lgkmcnt(0)
	v_lshlrev_b64 v[130:131], 11, v[246:247]
	v_add_f32_e32 v0, v132, v0
	v_mul_f32_e32 v132, v125, v125
	v_lshl_add_u64 v[130:131], s[58:59], 0, v[130:131]
	v_fmac_f32_e32 v132, v124, v124
	v_lshl_add_u64 v[130:131], v[232:233], 1, v[130:131]
	flat_store_dwordx4 v[244:245], v[126:129]
	flat_store_dwordx4 v[244:245], v[122:125] offset:16
	v_add_f32_e32 v0, v132, v0
	v_pk_mul_f32 v[128:129], v[80:81], v[128:129]
	v_pk_mul_f32 v[126:127], v[78:79], v[126:127]
	v_pk_mul_f32 v[132:133], v[76:77], v[124:125]
	v_pk_mul_f32 v[124:125], v[74:75], v[122:123]
	v_cvt_pk_bf16_f32 v122, v126, v127
	v_cvt_pk_bf16_f32 v123, v128, v129
	v_pk_add_f32 v[120:121], v[184:185], v[120:121]
	v_pk_add_f32 v[118:119], v[182:183], v[118:119]
	v_cvt_pk_bf16_f32 v124, v124, v125
	v_cvt_pk_bf16_f32 v125, v132, v133
	flat_store_dwordx4 v[130:131], v[122:125]
	v_pk_add_f32 v[114:115], v[178:179], v[114:115]
	v_pk_add_f32 v[116:117], v[180:181], v[116:117]
	v_mul_f32_e32 v122, v119, v119
	v_mul_f32_e32 v123, v121, v121
	v_fmac_f32_e32 v122, v118, v118
	v_fmac_f32_e32 v123, v120, v120
	v_add_f32_e32 v122, v122, v123
	v_mul_f32_e32 v123, v115, v115
	v_fmac_f32_e32 v123, v114, v114
	v_add_f32_e32 v122, v123, v122
	v_mul_f32_e32 v123, v117, v117
	v_fmac_f32_e32 v123, v116, v116
	v_add_f32_e32 v122, v123, v122
	v_add_f32_e32 v0, v0, v122
	flat_store_dwordx4 v[244:245], v[118:121] offset:512
	flat_store_dwordx4 v[244:245], v[114:117] offset:528
	v_pk_mul_f32 v[124:125], v[66:67], v[114:115]
	v_pk_mul_f32 v[118:119], v[70:71], v[118:119]
	v_pk_mul_f32 v[120:121], v[72:73], v[120:121]
	s_nop 1
	v_mov_b32_e32 v126, v0
	s_nop 1
	v_permlane16_swap_b32_e32 v0, v126
	v_add_f32_e32 v0, v0, v126
	v_mov_b32_e32 v114, v0
	s_nop 1
	v_permlane32_swap_b32_e32 v0, v114
	v_add_f32_e32 v0, v0, v114
	v_pk_mul_f32 v[122:123], v[68:69], v[116:117]
	v_cvt_pk_bf16_f32 v116, v118, v119
	v_cvt_pk_bf16_f32 v117, v120, v121
	v_cvt_pk_bf16_f32 v118, v124, v125
	s_nop 0
	v_cvt_pk_bf16_f32 v119, v122, v123
	flat_store_dwordx4 v[130:131], v[116:119] offset:256
	s_and_saveexec_b64 s[4:5], vcc
	s_cbranch_execz .LBB0_1102
	flat_atomic_add_f32 v[194:195], v0 offset:64
; __device__ __forceinline__ float lane_xor(float v, int lane, int o) { return __builtin_bit_cast(float, __builtin_amdgcn_ds_bpermute((lane ^ o) << 2, __builtin_bit_cast(int, v))); }
; __device__ __forceinline__ unsigned cvt_pk_bf16(float lo, float hi) { unsigned r; asm volatile("v_cvt_pk_bf16_f32 %0, %1, %2" : "=v"(r) : "v"(lo), "v"(hi)); return r; }
;     __device__ __forceinline__ void operator()(const f32x4 (&acc)[2][2][4][2], const Unit& u, int wr, int wc, int fr_in, int fq_in) const {
;     ...
;             for (int m = 0; m < 4; ++m) {
;                 const int row = row0 + ai * HALF + m * 16;
;                 bf16_t* xp = XN + (size_t)row * DM + col0;
;                 float sq = 0.f;
; #pragma unroll
;                 for (int bj = 0; bj < 2; ++bj) {
;                     const f32x4 a = hv[m][bj][0] + acc[ai][bj][m][0] * alpha, b = hv[m][bj][1] + acc[ai][bj][m][1] * alpha;
;                     *(f32x4*)(hp[m] + bj * HALF) = a; *(f32x4*)(hp[m] + bj * HALF + 4) = b;
;                     sq += (a[0] * a[0] + a[1] * a[1]) + (a[2] * a[2] + a[3] * a[3]) + (b[0] * b[0] + b[1] * b[1]) + (b[2] * b[2] + b[3] * b[3]);
;                     const f32x4 xa = a * gv[bj][0], xb = b * gv[bj][1];
;                     u32x4 w; w.x = cvt_pk_bf16(xa[0], xa[1]); w.y = cvt_pk_bf16(xa[2], xa[3]); w.z = cvt_pk_bf16(xb[0], xb[1]); w.w = cvt_pk_bf16(xb[2], xb[3]);
;                     *(u32x4*)(xp + bj * HALF) = w;
;                 }
;                 sq += lane_xor(sq, lane, 16); sq += lane_xor(sq, lane, 32);
;                 if (fq == 0) atomicAdd(SSout + row, sq);
;             }
.LBB0_1102:
	s_or_b64 exec, exec, s[4:5]
	v_pk_add_f32 v[112:113], v[176:177], v[112:113]
	v_pk_add_f32 v[110:111], v[174:175], v[110:111]
	v_mul_f32_e32 v116, v113, v113
	v_mul_f32_e32 v0, v111, v111
	v_pk_add_f32 v[106:107], v[170:171], v[106:107]
	v_fmac_f32_e32 v0, v110, v110
	v_fmac_f32_e32 v116, v112, v112
	v_add_f32_e32 v0, v0, v116
	v_mul_f32_e32 v116, v107, v107
	v_ashrrev_i32_e32 v243, 31, v242
	v_pk_add_f32 v[108:109], v[172:173], v[108:109]
	v_fmac_f32_e32 v116, v106, v106
	s_waitcnt lgkmcnt(0)
	v_lshlrev_b64 v[114:115], 11, v[242:243]
	v_add_f32_e32 v0, v116, v0
	v_mul_f32_e32 v116, v109, v109
	v_lshl_add_u64 v[114:115], s[58:59], 0, v[114:115]
	v_fmac_f32_e32 v116, v108, v108
	v_lshl_add_u64 v[114:115], v[232:233], 1, v[114:115]
	flat_store_dwordx4 v[240:241], v[110:113]
	flat_store_dwordx4 v[240:241], v[106:109] offset:16
	v_add_f32_e32 v0, v116, v0
	v_pk_mul_f32 v[112:113], v[80:81], v[112:113]
	v_pk_mul_f32 v[110:111], v[78:79], v[110:111]
	v_pk_mul_f32 v[116:117], v[76:77], v[108:109]
	v_pk_mul_f32 v[108:109], v[74:75], v[106:107]
	v_cvt_pk_bf16_f32 v106, v110, v111
	v_cvt_pk_bf16_f32 v107, v112, v113
	v_pk_add_f32 v[104:105], v[168:169], v[104:105]
	v_pk_add_f32 v[102:103], v[166:167], v[102:103]
	v_cvt_pk_bf16_f32 v108, v108, v109
	v_cvt_pk_bf16_f32 v109, v116, v117
	flat_store_dwordx4 v[114:115], v[106:109]
	v_pk_add_f32 v[98:99], v[162:163], v[98:99]
	v_pk_add_f32 v[100:101], v[164:165], v[100:101]
	v_mul_f32_e32 v106, v103, v103
	v_mul_f32_e32 v107, v105, v105
	v_fmac_f32_e32 v106, v102, v102
	v_fmac_f32_e32 v107, v104, v104
	v_add_f32_e32 v106, v106, v107
	v_mul_f32_e32 v107, v99, v99
	v_fmac_f32_e32 v107, v98, v98
	v_add_f32_e32 v106, v107, v106
	v_mul_f32_e32 v107, v101, v101
	v_fmac_f32_e32 v107, v100, v100
	v_add_f32_e32 v106, v107, v106
	v_add_f32_e32 v0, v0, v106
	flat_store_dwordx4 v[240:241], v[102:105] offset:512
	flat_store_dwordx4 v[240:241], v[98:101] offset:528
	v_pk_mul_f32 v[108:109], v[66:67], v[98:99]
	v_pk_mul_f32 v[102:103], v[70:71], v[102:103]
	v_pk_mul_f32 v[104:105], v[72:73], v[104:105]
	s_nop 1
	v_mov_b32_e32 v110, v0
	s_nop 1
	v_permlane16_swap_b32_e32 v0, v110
	v_add_f32_e32 v0, v0, v110
	v_mov_b32_e32 v98, v0
	s_nop 1
	v_permlane32_swap_b32_e32 v0, v98
	v_add_f32_e32 v0, v0, v98
	v_pk_mul_f32 v[106:107], v[68:69], v[100:101]
	v_cvt_pk_bf16_f32 v100, v102, v103
	v_cvt_pk_bf16_f32 v101, v104, v105
	v_cvt_pk_bf16_f32 v102, v108, v109
	s_nop 0
	v_cvt_pk_bf16_f32 v103, v106, v107
	flat_store_dwordx4 v[114:115], v[100:103] offset:256
	s_and_saveexec_b64 s[4:5], vcc
	s_cbranch_execz .LBB0_1104
	flat_atomic_add_f32 v[194:195], v0 offset:128
.LBB0_1104:
	s_or_b64 exec, exec, s[4:5]
	v_pk_add_f32 v[96:97], v[160:161], v[96:97]
	v_pk_add_f32 v[94:95], v[158:159], v[94:95]
	v_mul_f32_e32 v100, v97, v97
	v_mul_f32_e32 v0, v95, v95
	v_pk_add_f32 v[90:91], v[154:155], v[90:91]
	v_fmac_f32_e32 v0, v94, v94
	v_fmac_f32_e32 v100, v96, v96
	v_add_f32_e32 v0, v0, v100
	v_mul_f32_e32 v100, v91, v91
	v_ashrrev_i32_e32 v239, 31, v238
	v_pk_add_f32 v[92:93], v[156:157], v[92:93]
	v_fmac_f32_e32 v100, v90, v90
	s_waitcnt lgkmcnt(0)
	v_lshlrev_b64 v[98:99], 11, v[238:239]
	v_add_f32_e32 v0, v100, v0
	v_mul_f32_e32 v100, v93, v93
	v_lshl_add_u64 v[98:99], s[58:59], 0, v[98:99]
	v_fmac_f32_e32 v100, v92, v92
	v_lshl_add_u64 v[98:99], v[232:233], 1, v[98:99]
	flat_store_dwordx4 v[236:237], v[94:97]
	flat_store_dwordx4 v[236:237], v[90:93] offset:16
	v_add_f32_e32 v0, v100, v0
	v_pk_mul_f32 v[96:97], v[80:81], v[96:97]
	v_pk_mul_f32 v[94:95], v[78:79], v[94:95]
	v_pk_mul_f32 v[100:101], v[76:77], v[92:93]
	v_pk_mul_f32 v[92:93], v[74:75], v[90:91]
	v_cvt_pk_bf16_f32 v90, v94, v95
	v_cvt_pk_bf16_f32 v91, v96, v97
	v_pk_add_f32 v[88:89], v[152:153], v[88:89]
	v_pk_add_f32 v[86:87], v[150:151], v[86:87]
	v_cvt_pk_bf16_f32 v92, v92, v93
	v_cvt_pk_bf16_f32 v93, v100, v101
	flat_store_dwordx4 v[98:99], v[90:93]
	v_pk_add_f32 v[82:83], v[146:147], v[82:83]
	v_pk_add_f32 v[84:85], v[148:149], v[84:85]
	v_mul_f32_e32 v90, v87, v87
	v_mul_f32_e32 v91, v89, v89
	v_fmac_f32_e32 v90, v86, v86
	v_fmac_f32_e32 v91, v88, v88
	v_add_f32_e32 v90, v90, v91
	v_mul_f32_e32 v91, v83, v83
	v_fmac_f32_e32 v91, v82, v82
	v_add_f32_e32 v90, v91, v90
	v_mul_f32_e32 v91, v85, v85
	v_fmac_f32_e32 v91, v84, v84
	v_add_f32_e32 v90, v91, v90
	v_add_f32_e32 v0, v0, v90
	flat_store_dwordx4 v[236:237], v[86:89] offset:512
	flat_store_dwordx4 v[236:237], v[82:85] offset:528
	v_pk_mul_f32 v[92:93], v[66:67], v[82:83]
	v_pk_mul_f32 v[86:87], v[70:71], v[86:87]
	v_pk_mul_f32 v[88:89], v[72:73], v[88:89]
	s_nop 1
	v_mov_b32_e32 v94, v0
	s_nop 1
	v_permlane16_swap_b32_e32 v0, v94
	v_add_f32_e32 v0, v0, v94
	v_mov_b32_e32 v82, v0
	s_nop 1
	v_permlane32_swap_b32_e32 v0, v82
	v_add_f32_e32 v0, v0, v82
	v_pk_mul_f32 v[90:91], v[68:69], v[84:85]
	v_cvt_pk_bf16_f32 v84, v86, v87
	v_cvt_pk_bf16_f32 v85, v88, v89
	v_cvt_pk_bf16_f32 v86, v92, v93
	s_nop 0
	v_cvt_pk_bf16_f32 v87, v90, v91
	flat_store_dwordx4 v[98:99], v[84:87] offset:256
	s_and_saveexec_b64 s[4:5], vcc
	s_cbranch_execz .LBB0_1106
	flat_atomic_add_f32 v[194:195], v0 offset:192
; __device__ __forceinline__ float lane_xor(float v, int lane, int o) { return __builtin_bit_cast(float, __builtin_amdgcn_ds_bpermute((lane ^ o) << 2, __builtin_bit_cast(int, v))); }
; __device__ __forceinline__ unsigned cvt_pk_bf16(float lo, float hi) { unsigned r; asm volatile("v_cvt_pk_bf16_f32 %0, %1, %2" : "=v"(r) : "v"(lo), "v"(hi)); return r; }
;     __device__ __forceinline__ void operator()(const f32x4 (&acc)[2][2][4][2], const Unit& u, int wr, int wc, int fr_in, int fq_in) const {
;     ...
;             for (int m = 0; m < 4; ++m) { const int rw = row0 + ai * HALF + m * 16; hp[m] = hrow(LEAD, OUT, rw) + col0;
;                 const float* sp = hp[m];
;                 if (XP) { const int b = rw / LP, sl = rw - b * LP; if (sl >= 128) sp = (b < 2 ? XP + ((size_t)b * SEQ + (sl - 128)) * DM : XS + ((size_t)(b - 2) * SEQ + (sl - 128)) * DM) + col0; }
; #pragma unroll
;                 for (int bj = 0; bj < 2; ++bj) { hv[m][bj][0] = *(const f32x4*)(sp + bj * HALF); hv[m][bj][1] = *(const f32x4*)(sp + bj * HALF + 4); } }
; #pragma unroll
;             for (int m = 0; m < 4; ++m) {
;                 const int row = row0 + ai * HALF + m * 16;
;                 bf16_t* xp = XN + (size_t)row * DM + col0;
;                 float sq = 0.f;
; #pragma unroll
;                 for (int bj = 0; bj < 2; ++bj) {
;                     const f32x4 a = hv[m][bj][0] + acc[ai][bj][m][0] * alpha, b = hv[m][bj][1] + acc[ai][bj][m][1] * alpha;
;                     *(f32x4*)(hp[m] + bj * HALF) = a; *(f32x4*)(hp[m] + bj * HALF + 4) = b;
;                     sq += (a[0] * a[0] + a[1] * a[1]) + (a[2] * a[2] + a[3] * a[3]) + (b[0] * b[0] + b[1] * b[1]) + (b[2] * b[2] + b[3] * b[3]);
;                     const f32x4 xa = a * gv[bj][0], xb = b * gv[bj][1];
;                     u32x4 w; w.x = cvt_pk_bf16(xa[0], xa[1]); w.y = cvt_pk_bf16(xa[2], xa[3]); w.z = cvt_pk_bf16(xb[0], xb[1]); w.w = cvt_pk_bf16(xb[2], xb[3]);
;                     *(u32x4*)(xp + bj * HALF) = w;
;                 }
;                 sq += lane_xor(sq, lane, 16); sq += lane_xor(sq, lane, 32);
;                 if (fq == 0) atomicAdd(SSout + row, sq);
;             }
.LBB0_1106:
	s_or_b64 exec, exec, s[4:5]
	v_add_u32_e32 v160, 0x80, v234
	v_mul_hi_i32 v0, v160, s33
	s_waitcnt lgkmcnt(0)
	v_lshrrev_b32_e32 v82, 31, v0
	v_ashrrev_i32_e32 v0, 12, v0
	v_add_u32_e32 v82, v0, v82
	v_mad_i32_i24 v0, v82, s51, v160
	v_cmp_lt_i32_e64 s[4:5], s3, v0
	s_and_saveexec_b64 s[36:37], s[4:5]
	s_xor_b64 s[4:5], exec, s[36:37]
	v_mul_i32_i24_e32 v0, 0xffffdf80, v82
	v_ashrrev_i32_e32 v83, 31, v82
	v_add_u32_e32 v0, v0, v234
	v_lshlrev_b64 v[82:83], 25, v[82:83]
	v_lshl_add_u64 v[86:87], s[56:57], 0, v[82:83]
	v_mov_b64_e32 v[84:85], v[0:1]
	s_andn2_saveexec_b64 s[4:5], s[4:5]
	v_lshl_add_u32 v84, v82, 7, v0
	v_ashrrev_i32_e32 v85, 31, v84
	v_mov_b64_e32 v[86:87], s[18:19]
	s_or_b64 exec, exec, s[4:5]
	v_lshlrev_b64 v[82:83], 12, v[84:85]
	v_lshl_add_u64 v[82:83], v[86:87], 0, v[82:83]
	v_lshl_add_u64 v[158:159], v[232:233], 2, v[82:83]
	flat_load_dwordx4 v[142:145], v[158:159]
	flat_load_dwordx4 v[138:141], v[158:159] offset:16
	flat_load_dwordx4 v[134:137], v[158:159] offset:512
	flat_load_dwordx4 v[130:133], v[158:159] offset:528
	v_add_u32_e32 v156, 0x90, v234
	v_mul_hi_i32 v0, v156, s33
	v_lshrrev_b32_e32 v82, 31, v0
	v_ashrrev_i32_e32 v0, 12, v0
	v_add_u32_e32 v82, v0, v82
	v_mad_i32_i24 v0, v82, s51, v156
	v_cmp_lt_i32_e64 s[4:5], s3, v0
	s_and_saveexec_b64 s[36:37], s[4:5]
	s_xor_b64 s[4:5], exec, s[36:37]
	v_ashrrev_i32_e32 v83, 31, v82
	v_add_u32_e32 v0, 0xffffff80, v0
	v_lshlrev_b64 v[82:83], 25, v[82:83]
	v_lshl_add_u64 v[86:87], s[56:57], 0, v[82:83]
	v_mov_b64_e32 v[84:85], v[0:1]
	s_andn2_saveexec_b64 s[4:5], s[4:5]
	v_lshl_add_u32 v84, v82, 7, v0
	v_ashrrev_i32_e32 v85, 31, v84
	v_mov_b64_e32 v[86:87], s[18:19]
	s_or_b64 exec, exec, s[4:5]
	v_lshlrev_b64 v[82:83], 12, v[84:85]
	v_lshl_add_u64 v[82:83], v[86:87], 0, v[82:83]
	v_lshl_add_u64 v[154:155], v[232:233], 2, v[82:83]
	flat_load_dwordx4 v[126:129], v[154:155]
	flat_load_dwordx4 v[122:125], v[154:155] offset:16
	flat_load_dwordx4 v[118:121], v[154:155] offset:512
	flat_load_dwordx4 v[114:117], v[154:155] offset:528
	v_add_u32_e32 v152, 0xa0, v234
	v_mul_hi_i32 v0, v152, s33
	v_lshrrev_b32_e32 v82, 31, v0
	v_ashrrev_i32_e32 v0, 12, v0
	v_add_u32_e32 v82, v0, v82
	v_mad_i32_i24 v0, v82, s51, v152
	v_cmp_lt_i32_e64 s[4:5], s3, v0
	s_and_saveexec_b64 s[36:37], s[4:5]
	s_xor_b64 s[4:5], exec, s[36:37]
	v_ashrrev_i32_e32 v83, 31, v82
	v_add_u32_e32 v0, 0xffffff80, v0
	v_lshlrev_b64 v[82:83], 25, v[82:83]
	v_lshl_add_u64 v[86:87], s[56:57], 0, v[82:83]
	v_mov_b64_e32 v[84:85], v[0:1]
	s_andn2_saveexec_b64 s[4:5], s[4:5]
	v_lshl_add_u32 v84, v82, 7, v0
	v_ashrrev_i32_e32 v85, 31, v84
	v_mov_b64_e32 v[86:87], s[18:19]
	s_or_b64 exec, exec, s[4:5]
	v_lshlrev_b64 v[82:83], 12, v[84:85]
	v_lshl_add_u64 v[82:83], v[86:87], 0, v[82:83]
	v_lshl_add_u64 v[150:151], v[232:233], 2, v[82:83]
	flat_load_dwordx4 v[110:113], v[150:151]
	flat_load_dwordx4 v[106:109], v[150:151] offset:16
	flat_load_dwordx4 v[102:105], v[150:151] offset:512
	flat_load_dwordx4 v[98:101], v[150:151] offset:528
	v_add_u32_e32 v148, 0xb0, v234
	v_mul_hi_i32 v0, v148, s33
	v_lshrrev_b32_e32 v82, 31, v0
	v_ashrrev_i32_e32 v0, 12, v0
	v_add_u32_e32 v82, v0, v82
	v_mad_i32_i24 v0, v82, s51, v148
	v_cmp_lt_i32_e64 s[4:5], s3, v0
	s_and_saveexec_b64 s[36:37], s[4:5]
	s_xor_b64 s[4:5], exec, s[36:37]
	v_ashrrev_i32_e32 v83, 31, v82
	v_add_u32_e32 v0, 0xffffff80, v0
	v_lshlrev_b64 v[82:83], 25, v[82:83]
	v_lshl_add_u64 v[86:87], s[56:57], 0, v[82:83]
	v_mov_b64_e32 v[84:85], v[0:1]
	s_andn2_saveexec_b64 s[4:5], s[4:5]
	v_lshl_add_u32 v84, v82, 7, v0
	v_ashrrev_i32_e32 v85, 31, v84
	v_mov_b64_e32 v[86:87], s[18:19]
	s_or_b64 exec, exec, s[4:5]
	v_lshlrev_b64 v[82:83], 12, v[84:85]
	v_lshl_add_u64 v[82:83], v[86:87], 0, v[82:83]
	v_lshl_add_u64 v[146:147], v[232:233], 2, v[82:83]
	flat_load_dwordx4 v[94:97], v[146:147]
	flat_load_dwordx4 v[90:93], v[146:147] offset:16
	flat_load_dwordx4 v[86:89], v[146:147] offset:512
	flat_load_dwordx4 v[82:85], v[146:147] offset:528
	s_waitcnt vmcnt(0) lgkmcnt(0)
	v_pk_add_f32 v[64:65], v[144:145], v[64:65]
	v_pk_add_f32 v[62:63], v[142:143], v[62:63]
	v_pk_add_f32 v[58:59], v[138:139], v[58:59]
	v_mul_f32_e32 v0, v63, v63
	v_mul_f32_e32 v138, v65, v65
	v_fmac_f32_e32 v0, v62, v62
	v_fmac_f32_e32 v138, v64, v64
	v_add_f32_e32 v0, v0, v138
	v_mul_f32_e32 v138, v59, v59
	v_ashrrev_i32_e32 v161, 31, v160
	v_pk_add_f32 v[60:61], v[140:141], v[60:61]
	v_fmac_f32_e32 v138, v58, v58
	v_lshlrev_b64 v[160:161], 11, v[160:161]
	v_add_f32_e32 v0, v138, v0
	v_mul_f32_e32 v138, v61, v61
	v_lshl_add_u64 v[160:161], s[58:59], 0, v[160:161]
	v_fmac_f32_e32 v138, v60, v60
	v_lshl_add_u64 v[160:161], v[232:233], 1, v[160:161]
	flat_store_dwordx4 v[158:159], v[62:65]
	flat_store_dwordx4 v[158:159], v[58:61] offset:16
	v_add_f32_e32 v0, v138, v0
	v_pk_mul_f32 v[64:65], v[80:81], v[64:65]
	v_pk_mul_f32 v[62:63], v[78:79], v[62:63]
	v_pk_mul_f32 v[138:139], v[76:77], v[60:61]
	v_pk_mul_f32 v[60:61], v[74:75], v[58:59]
	v_cvt_pk_bf16_f32 v58, v62, v63
	v_cvt_pk_bf16_f32 v59, v64, v65
	v_pk_add_f32 v[56:57], v[136:137], v[56:57]
	v_pk_add_f32 v[54:55], v[134:135], v[54:55]
	v_cvt_pk_bf16_f32 v60, v60, v61
	v_cvt_pk_bf16_f32 v61, v138, v139
	flat_store_dwordx4 v[160:161], v[58:61]
	v_pk_add_f32 v[50:51], v[130:131], v[50:51]
	v_pk_add_f32 v[52:53], v[132:133], v[52:53]
	v_mul_f32_e32 v58, v55, v55
	v_mul_f32_e32 v59, v57, v57
	v_fmac_f32_e32 v58, v54, v54
	v_fmac_f32_e32 v59, v56, v56
	v_add_f32_e32 v58, v58, v59
	v_mul_f32_e32 v59, v51, v51
	v_fmac_f32_e32 v59, v50, v50
	v_add_f32_e32 v58, v59, v58
	v_mul_f32_e32 v59, v53, v53
	v_fmac_f32_e32 v59, v52, v52
	v_add_f32_e32 v58, v59, v58
	v_add_f32_e32 v0, v0, v58
	flat_store_dwordx4 v[158:159], v[54:57] offset:512
	flat_store_dwordx4 v[158:159], v[50:53] offset:528
	v_pk_mul_f32 v[60:61], v[66:67], v[50:51]
	v_pk_mul_f32 v[54:55], v[70:71], v[54:55]
	v_pk_mul_f32 v[56:57], v[72:73], v[56:57]
	s_nop 1
	v_mov_b32_e32 v62, v0
	s_nop 1
	v_permlane16_swap_b32_e32 v0, v62
	v_add_f32_e32 v0, v0, v62
	v_mov_b32_e32 v50, v0
	s_nop 1
	v_permlane32_swap_b32_e32 v0, v50
	v_add_f32_e32 v0, v0, v50
	v_pk_mul_f32 v[58:59], v[68:69], v[52:53]
	v_cvt_pk_bf16_f32 v52, v54, v55
	v_cvt_pk_bf16_f32 v53, v56, v57
	v_cvt_pk_bf16_f32 v54, v60, v61
	s_nop 0
	v_cvt_pk_bf16_f32 v55, v58, v59
	flat_store_dwordx4 v[160:161], v[52:55] offset:256
	s_and_saveexec_b64 s[4:5], vcc
	s_cbranch_execz .LBB0_1124
	flat_atomic_add_f32 v[194:195], v0 offset:512
; __device__ __forceinline__ float lane_xor(float v, int lane, int o) { return __builtin_bit_cast(float, __builtin_amdgcn_ds_bpermute((lane ^ o) << 2, __builtin_bit_cast(int, v))); }
; __device__ __forceinline__ unsigned cvt_pk_bf16(float lo, float hi) { unsigned r; asm volatile("v_cvt_pk_bf16_f32 %0, %1, %2" : "=v"(r) : "v"(lo), "v"(hi)); return r; }
;     __device__ __forceinline__ void operator()(const f32x4 (&acc)[2][2][4][2], const Unit& u, int wr, int wc, int fr_in, int fq_in) const {
;     ...
;             for (int m = 0; m < 4; ++m) {
;                 const int row = row0 + ai * HALF + m * 16;
;                 bf16_t* xp = XN + (size_t)row * DM + col0;
;                 float sq = 0.f;
; #pragma unroll
;                 for (int bj = 0; bj < 2; ++bj) {
;                     const f32x4 a = hv[m][bj][0] + acc[ai][bj][m][0] * alpha, b = hv[m][bj][1] + acc[ai][bj][m][1] * alpha;
;                     *(f32x4*)(hp[m] + bj * HALF) = a; *(f32x4*)(hp[m] + bj * HALF + 4) = b;
;                     sq += (a[0] * a[0] + a[1] * a[1]) + (a[2] * a[2] + a[3] * a[3]) + (b[0] * b[0] + b[1] * b[1]) + (b[2] * b[2] + b[3] * b[3]);
;                     const f32x4 xa = a * gv[bj][0], xb = b * gv[bj][1];
;                     u32x4 w; w.x = cvt_pk_bf16(xa[0], xa[1]); w.y = cvt_pk_bf16(xa[2], xa[3]); w.z = cvt_pk_bf16(xb[0], xb[1]); w.w = cvt_pk_bf16(xb[2], xb[3]);
;                     *(u32x4*)(xp + bj * HALF) = w;
;                 }
;                 sq += lane_xor(sq, lane, 16); sq += lane_xor(sq, lane, 32);
;                 if (fq == 0) atomicAdd(SSout + row, sq);
;             }
.LBB0_1124:
	s_or_b64 exec, exec, s[4:5]
	v_pk_add_f32 v[48:49], v[128:129], v[48:49]
	v_pk_add_f32 v[46:47], v[126:127], v[46:47]
	v_mul_f32_e32 v52, v49, v49
	v_mul_f32_e32 v0, v47, v47
	v_pk_add_f32 v[42:43], v[122:123], v[42:43]
	v_fmac_f32_e32 v0, v46, v46
	v_fmac_f32_e32 v52, v48, v48
	v_add_f32_e32 v0, v0, v52
	v_mul_f32_e32 v52, v43, v43
	v_ashrrev_i32_e32 v157, 31, v156
	v_pk_add_f32 v[44:45], v[124:125], v[44:45]
	v_fmac_f32_e32 v52, v42, v42
	s_waitcnt lgkmcnt(0)
	v_lshlrev_b64 v[50:51], 11, v[156:157]
	v_add_f32_e32 v0, v52, v0
	v_mul_f32_e32 v52, v45, v45
	v_lshl_add_u64 v[50:51], s[58:59], 0, v[50:51]
	v_fmac_f32_e32 v52, v44, v44
	v_lshl_add_u64 v[50:51], v[232:233], 1, v[50:51]
	flat_store_dwordx4 v[154:155], v[46:49]
	flat_store_dwordx4 v[154:155], v[42:45] offset:16
	v_add_f32_e32 v0, v52, v0
	v_pk_mul_f32 v[48:49], v[80:81], v[48:49]
	v_pk_mul_f32 v[46:47], v[78:79], v[46:47]
	v_pk_mul_f32 v[52:53], v[76:77], v[44:45]
	v_pk_mul_f32 v[44:45], v[74:75], v[42:43]
	v_cvt_pk_bf16_f32 v42, v46, v47
	v_cvt_pk_bf16_f32 v43, v48, v49
	v_pk_add_f32 v[40:41], v[120:121], v[40:41]
	v_pk_add_f32 v[38:39], v[118:119], v[38:39]
	v_cvt_pk_bf16_f32 v44, v44, v45
	v_cvt_pk_bf16_f32 v45, v52, v53
	flat_store_dwordx4 v[50:51], v[42:45]
	v_pk_add_f32 v[34:35], v[114:115], v[34:35]
	v_pk_add_f32 v[36:37], v[116:117], v[36:37]
	v_mul_f32_e32 v42, v39, v39
	v_mul_f32_e32 v43, v41, v41
	v_fmac_f32_e32 v42, v38, v38
	v_fmac_f32_e32 v43, v40, v40
	v_add_f32_e32 v42, v42, v43
	v_mul_f32_e32 v43, v35, v35
	v_fmac_f32_e32 v43, v34, v34
	v_add_f32_e32 v42, v43, v42
	v_mul_f32_e32 v43, v37, v37
	v_fmac_f32_e32 v43, v36, v36
	v_add_f32_e32 v42, v43, v42
	v_add_f32_e32 v0, v0, v42
	flat_store_dwordx4 v[154:155], v[38:41] offset:512
	flat_store_dwordx4 v[154:155], v[34:37] offset:528
	v_pk_mul_f32 v[44:45], v[66:67], v[34:35]
	v_pk_mul_f32 v[38:39], v[70:71], v[38:39]
	v_pk_mul_f32 v[40:41], v[72:73], v[40:41]
	s_nop 1
	v_mov_b32_e32 v46, v0
	s_nop 1
	v_permlane16_swap_b32_e32 v0, v46
	v_add_f32_e32 v0, v0, v46
	v_mov_b32_e32 v34, v0
	s_nop 1
	v_permlane32_swap_b32_e32 v0, v34
	v_add_f32_e32 v0, v0, v34
	v_pk_mul_f32 v[42:43], v[68:69], v[36:37]
	v_cvt_pk_bf16_f32 v36, v38, v39
	v_cvt_pk_bf16_f32 v37, v40, v41
	v_cvt_pk_bf16_f32 v38, v44, v45
	s_nop 0
	v_cvt_pk_bf16_f32 v39, v42, v43
	flat_store_dwordx4 v[50:51], v[36:39] offset:256
	s_and_saveexec_b64 s[4:5], vcc
	s_cbranch_execz .LBB0_1126
	flat_atomic_add_f32 v[194:195], v0 offset:576
; __device__ __forceinline__ float lane_xor(float v, int lane, int o) { return __builtin_bit_cast(float, __builtin_amdgcn_ds_bpermute((lane ^ o) << 2, __builtin_bit_cast(int, v))); }
; __device__ __forceinline__ unsigned cvt_pk_bf16(float lo, float hi) { unsigned r; asm volatile("v_cvt_pk_bf16_f32 %0, %1, %2" : "=v"(r) : "v"(lo), "v"(hi)); return r; }
;     __device__ __forceinline__ void operator()(const f32x4 (&acc)[2][2][4][2], const Unit& u, int wr, int wc, int fr_in, int fq_in) const {
;     ...
;             for (int m = 0; m < 4; ++m) {
;                 const int row = row0 + ai * HALF + m * 16;
;                 bf16_t* xp = XN + (size_t)row * DM + col0;
;                 float sq = 0.f;
; #pragma unroll
;                 for (int bj = 0; bj < 2; ++bj) {
;                     const f32x4 a = hv[m][bj][0] + acc[ai][bj][m][0] * alpha, b = hv[m][bj][1] + acc[ai][bj][m][1] * alpha;
;                     *(f32x4*)(hp[m] + bj * HALF) = a; *(f32x4*)(hp[m] + bj * HALF + 4) = b;
;                     sq += (a[0] * a[0] + a[1] * a[1]) + (a[2] * a[2] + a[3] * a[3]) + (b[0] * b[0] + b[1] * b[1]) + (b[2] * b[2] + b[3] * b[3]);
;                     const f32x4 xa = a * gv[bj][0], xb = b * gv[bj][1];
;                     u32x4 w; w.x = cvt_pk_bf16(xa[0], xa[1]); w.y = cvt_pk_bf16(xa[2], xa[3]); w.z = cvt_pk_bf16(xb[0], xb[1]); w.w = cvt_pk_bf16(xb[2], xb[3]);
;                     *(u32x4*)(xp + bj * HALF) = w;
;                 }
;                 sq += lane_xor(sq, lane, 16); sq += lane_xor(sq, lane, 32);
;                 if (fq == 0) atomicAdd(SSout + row, sq);
;             }
.LBB0_1126:
	s_or_b64 exec, exec, s[4:5]
	v_pk_add_f32 v[32:33], v[112:113], v[32:33]
	v_pk_add_f32 v[30:31], v[110:111], v[30:31]
	v_mul_f32_e32 v36, v33, v33
	v_mul_f32_e32 v0, v31, v31
	v_pk_add_f32 v[26:27], v[106:107], v[26:27]
	v_fmac_f32_e32 v0, v30, v30
	v_fmac_f32_e32 v36, v32, v32
	v_add_f32_e32 v0, v0, v36
	v_mul_f32_e32 v36, v27, v27
	v_ashrrev_i32_e32 v153, 31, v152
	v_pk_add_f32 v[28:29], v[108:109], v[28:29]
	v_fmac_f32_e32 v36, v26, v26
	s_waitcnt lgkmcnt(0)
	v_lshlrev_b64 v[34:35], 11, v[152:153]
	v_add_f32_e32 v0, v36, v0
	v_mul_f32_e32 v36, v29, v29
	v_lshl_add_u64 v[34:35], s[58:59], 0, v[34:35]
	v_fmac_f32_e32 v36, v28, v28
	v_lshl_add_u64 v[34:35], v[232:233], 1, v[34:35]
	flat_store_dwordx4 v[150:151], v[30:33]
	flat_store_dwordx4 v[150:151], v[26:29] offset:16
	v_add_f32_e32 v0, v36, v0
	v_pk_mul_f32 v[32:33], v[80:81], v[32:33]
	v_pk_mul_f32 v[30:31], v[78:79], v[30:31]
	v_pk_mul_f32 v[36:37], v[76:77], v[28:29]
	v_pk_mul_f32 v[28:29], v[74:75], v[26:27]
	v_cvt_pk_bf16_f32 v26, v30, v31
	v_cvt_pk_bf16_f32 v27, v32, v33
	v_pk_add_f32 v[24:25], v[104:105], v[24:25]
	v_pk_add_f32 v[22:23], v[102:103], v[22:23]
	v_cvt_pk_bf16_f32 v28, v28, v29
	v_cvt_pk_bf16_f32 v29, v36, v37
	flat_store_dwordx4 v[34:35], v[26:29]
	v_pk_add_f32 v[18:19], v[98:99], v[18:19]
	v_pk_add_f32 v[20:21], v[100:101], v[20:21]
	v_mul_f32_e32 v26, v23, v23
	v_mul_f32_e32 v27, v25, v25
	v_fmac_f32_e32 v26, v22, v22
	v_fmac_f32_e32 v27, v24, v24
	v_add_f32_e32 v26, v26, v27
	v_mul_f32_e32 v27, v19, v19
	v_fmac_f32_e32 v27, v18, v18
	v_add_f32_e32 v26, v27, v26
	v_mul_f32_e32 v27, v21, v21
	v_fmac_f32_e32 v27, v20, v20
	v_add_f32_e32 v26, v27, v26
	v_add_f32_e32 v0, v0, v26
	flat_store_dwordx4 v[150:151], v[22:25] offset:512
	flat_store_dwordx4 v[150:151], v[18:21] offset:528
	v_pk_mul_f32 v[28:29], v[66:67], v[18:19]
	v_pk_mul_f32 v[22:23], v[70:71], v[22:23]
	v_pk_mul_f32 v[24:25], v[72:73], v[24:25]
	s_nop 1
	v_mov_b32_e32 v30, v0
	s_nop 1
	v_permlane16_swap_b32_e32 v0, v30
	v_add_f32_e32 v0, v0, v30
	v_mov_b32_e32 v18, v0
	s_nop 1
	v_permlane32_swap_b32_e32 v0, v18
	v_add_f32_e32 v0, v0, v18
	v_pk_mul_f32 v[26:27], v[68:69], v[20:21]
	v_cvt_pk_bf16_f32 v20, v22, v23
	v_cvt_pk_bf16_f32 v21, v24, v25
	v_cvt_pk_bf16_f32 v22, v28, v29
	s_nop 0
	v_cvt_pk_bf16_f32 v23, v26, v27
	flat_store_dwordx4 v[34:35], v[20:23] offset:256
	s_and_saveexec_b64 s[4:5], vcc
	s_cbranch_execz .LBB0_1128
	flat_atomic_add_f32 v[194:195], v0 offset:640
.LBB0_1128:
	s_or_b64 exec, exec, s[4:5]
	v_pk_add_f32 v[16:17], v[96:97], v[16:17]
	v_pk_add_f32 v[14:15], v[94:95], v[14:15]
	v_mul_f32_e32 v20, v17, v17
	v_mul_f32_e32 v0, v15, v15
	v_pk_add_f32 v[10:11], v[90:91], v[10:11]
	v_fmac_f32_e32 v0, v14, v14
	v_fmac_f32_e32 v20, v16, v16
	v_add_f32_e32 v0, v0, v20
	v_mul_f32_e32 v20, v11, v11
	v_ashrrev_i32_e32 v149, 31, v148
	v_pk_add_f32 v[12:13], v[92:93], v[12:13]
	v_fmac_f32_e32 v20, v10, v10
	s_waitcnt lgkmcnt(0)
	v_lshlrev_b64 v[18:19], 11, v[148:149]
	v_add_f32_e32 v0, v20, v0
	v_mul_f32_e32 v20, v13, v13
	v_lshl_add_u64 v[18:19], s[58:59], 0, v[18:19]
	v_fmac_f32_e32 v20, v12, v12
	v_lshl_add_u64 v[18:19], v[232:233], 1, v[18:19]
	flat_store_dwordx4 v[146:147], v[14:17]
	flat_store_dwordx4 v[146:147], v[10:13] offset:16
	v_add_f32_e32 v0, v20, v0
	v_pk_mul_f32 v[16:17], v[80:81], v[16:17]
	v_pk_mul_f32 v[14:15], v[78:79], v[14:15]
	v_pk_mul_f32 v[20:21], v[76:77], v[12:13]
	v_pk_mul_f32 v[12:13], v[74:75], v[10:11]
	v_cvt_pk_bf16_f32 v10, v14, v15
	v_cvt_pk_bf16_f32 v11, v16, v17
	v_pk_add_f32 v[8:9], v[88:89], v[8:9]
	v_pk_add_f32 v[6:7], v[86:87], v[6:7]
	v_cvt_pk_bf16_f32 v12, v12, v13
	v_cvt_pk_bf16_f32 v13, v20, v21
	flat_store_dwordx4 v[18:19], v[10:13]
	v_pk_add_f32 v[2:3], v[82:83], v[2:3]
	v_pk_add_f32 v[4:5], v[84:85], v[4:5]
	v_mul_f32_e32 v10, v7, v7
	v_mul_f32_e32 v11, v9, v9
	v_fmac_f32_e32 v10, v6, v6
	v_fmac_f32_e32 v11, v8, v8
	v_add_f32_e32 v10, v10, v11
	v_mul_f32_e32 v11, v3, v3
	v_fmac_f32_e32 v11, v2, v2
	v_add_f32_e32 v10, v11, v10
	v_mul_f32_e32 v11, v5, v5
	v_fmac_f32_e32 v11, v4, v4
	v_add_f32_e32 v10, v11, v10
	v_add_f32_e32 v0, v0, v10
	flat_store_dwordx4 v[146:147], v[6:9] offset:512
	flat_store_dwordx4 v[146:147], v[2:5] offset:528
	v_pk_mul_f32 v[12:13], v[66:67], v[2:3]
	v_pk_mul_f32 v[6:7], v[70:71], v[6:7]
	v_pk_mul_f32 v[8:9], v[72:73], v[8:9]
	s_nop 1
	v_mov_b32_e32 v14, v0
	s_nop 1
	v_permlane16_swap_b32_e32 v0, v14
	v_add_f32_e32 v0, v0, v14
	v_mov_b32_e32 v2, v0
	s_nop 1
	v_permlane32_swap_b32_e32 v0, v2
	v_add_f32_e32 v0, v0, v2
	v_pk_mul_f32 v[10:11], v[68:69], v[4:5]
	v_cvt_pk_bf16_f32 v4, v6, v7
	v_cvt_pk_bf16_f32 v5, v8, v9
	v_cvt_pk_bf16_f32 v6, v12, v13
	s_nop 0
	v_cvt_pk_bf16_f32 v7, v10, v11
	flat_store_dwordx4 v[18:19], v[4:7] offset:256
	s_and_saveexec_b64 s[4:5], vcc
	s_cbranch_execz .LBB0_1130
	flat_atomic_add_f32 v[194:195], v0 offset:704
